# v013 + residual GEMM epilogues (out-proj, down0, attn-out): serialized load-wait-store ladder replaced by 3-row-group prefetch ring with counted vmcnt
# speedup vs baseline: 1.0107x; 1.0107x over previous
.LBB0_1858:
	s_lshl_b32 s6, s6, 8
	v_mov_b32_e32 v143, v146
	v_mov_b32_e32 v166, v1
	s_lshl_b32 s17, s4, 8
	s_add_i32 s6, s6, s42
	s_or_b32 s17, s17, s43
	v_add_u32_e32 v144, s6, v143
	v_lshl_add_u32 v142, v166, 2, s17
	v_ashrrev_i32_e32 v145, 31, v144
	v_ashrrev_i32_e32 v143, 31, v142
	v_lshlrev_b64 v[152:153], 11, v[144:145]
	v_lshl_add_u64 v[156:157], v[152:153], 0, v[142:143]
	v_readlane_b32 s52, v254, 7
	v_lshlrev_b64 v[158:159], 2, v[156:157]
	v_readlane_b32 s53, v254, 8
	v_readlane_b32 s54, v254, 9
	v_readlane_b32 s55, v254, 10
	v_lshl_add_u64 v[160:161], s[52:53], 0, v[158:159]
	v_mov_b32_e32 v218, v160
	v_mov_b32_e32 v219, v161
	global_load_dwordx4 v[168:171], v[218:219], off nt
	global_load_dwordx4 v[172:175], v[218:219], off offset:64 nt
	global_load_dwordx4 v[176:179], v[218:219], off offset:512 nt
	global_load_dwordx4 v[180:183], v[218:219], off offset:576 nt
	s_mov_b32 s98, 0x20000
	s_mov_b32 s99, 0
	v_lshl_add_u64 v[216:217], v[218:219], 0, s[98:99]
	global_load_dwordx4 v[184:187], v[216:217], off nt
	global_load_dwordx4 v[188:191], v[216:217], off offset:64 nt
	global_load_dwordx4 v[192:195], v[216:217], off offset:512 nt
	global_load_dwordx4 v[196:199], v[216:217], off offset:576 nt
	s_mov_b32 s98, 0x40000
	s_mov_b32 s99, 0
	v_lshl_add_u64 v[216:217], v[218:219], 0, s[98:99]
	global_load_dwordx4 v[200:203], v[216:217], off nt
	global_load_dwordx4 v[204:207], v[216:217], off offset:64 nt
	global_load_dwordx4 v[208:211], v[216:217], off offset:512 nt
	global_load_dwordx4 v[212:215], v[216:217], off offset:576 nt
	v_readlane_b32 s56, v254, 11
	v_readlane_b32 s57, v254, 12
	v_readlane_b32 s58, v254, 13
	v_readlane_b32 s59, v254, 14
	v_readlane_b32 s60, v254, 15
	v_readlane_b32 s61, v254, 16
	v_readlane_b32 s62, v254, 17
	v_readlane_b32 s63, v254, 18
	v_readlane_b32 s64, v254, 19
	v_readlane_b32 s65, v254, 20
	v_readlane_b32 s66, v254, 21
	v_readlane_b32 s67, v254, 22
	v_readlane_b32 s52, v254, 32
	v_readlane_b32 s66, v254, 46
	v_readlane_b32 s67, v254, 47
	v_lshl_add_u64 v[162:163], v[156:157], 1, s[88:89]
	v_readlane_b32 s53, v254, 33
	v_lshl_add_u64 v[164:165], s[66:67], 0, v[158:159]
	v_readlane_b32 s54, v254, 34
	v_readlane_b32 s55, v254, 35
	v_readlane_b32 s56, v254, 36
	v_readlane_b32 s57, v254, 37
	v_readlane_b32 s58, v254, 38
	v_readlane_b32 s59, v254, 39
	v_readlane_b32 s60, v254, 40
	v_readlane_b32 s61, v254, 41
	v_readlane_b32 s62, v254, 42
	v_readlane_b32 s63, v254, 43
	v_readlane_b32 s64, v254, 44
	v_readlane_b32 s65, v254, 45
	s_waitcnt vmcnt(11)
	v_pk_add_f32 v[128:129], v[128:129], v[170:171]
	v_pk_add_f32 v[126:127], v[126:127], v[168:169]
	v_cvt_pk_bf16_f32 v169, v128, v129
	v_cvt_pk_bf16_f32 v168, v126, v127
	global_store_dwordx4 v[164:165], v[126:129], off nt
	global_store_dwordx2 v[162:163], v[168:169], off
	s_waitcnt vmcnt(12)
	v_pk_add_f32 v[124:125], v[124:125], v[174:175]
	v_pk_add_f32 v[122:123], v[122:123], v[172:173]
	v_cvt_pk_bf16_f32 v173, v124, v125
	v_cvt_pk_bf16_f32 v172, v122, v123
	global_store_dwordx4 v[164:165], v[122:125], off offset:64 nt
	global_store_dwordx2 v[162:163], v[172:173], off offset:32
	s_waitcnt vmcnt(13)
	v_pk_add_f32 v[178:179], v[120:121], v[178:179]
	v_pk_add_f32 v[176:177], v[118:119], v[176:177]
	v_cvt_pk_bf16_f32 v119, v178, v179
	v_cvt_pk_bf16_f32 v118, v176, v177
	global_store_dwordx4 v[164:165], v[176:179], off offset:512 nt
	global_store_dwordx2 v[162:163], v[118:119], off offset:256
	v_mul_f32_e32 v120, v127, v127
	v_mul_f32_e32 v121, v129, v129
	v_fmac_f32_e32 v120, v126, v126
	v_fmac_f32_e32 v121, v128, v128
	v_add_f32_e32 v120, v120, v121
	v_mul_f32_e32 v121, v123, v123
	v_mul_f32_e32 v123, v125, v125
	v_fmac_f32_e32 v121, v122, v122
	v_fmac_f32_e32 v123, v124, v124
	v_add_f32_e32 v121, v121, v123
	v_add_f32_e32 v120, v120, v121
	v_mul_f32_e32 v121, v177, v177
	v_mul_f32_e32 v122, v179, v179
	v_fmac_f32_e32 v121, v176, v176
	v_fmac_f32_e32 v122, v178, v178
	v_add_f32_e32 v121, v121, v122
	v_and_b32_e32 v119, 64, v151
	v_add_f32_e32 v124, v120, v121
	v_xor_b32_e32 v118, 16, v151
	v_add_u32_e32 v119, 64, v119
	v_cmp_lt_i32_e32 vcc, v118, v119
	v_xor_b32_e32 v160, 32, v151
	s_waitcnt vmcnt(14)
	v_pk_add_f32 v[122:123], v[116:117], v[182:183]
	v_pk_add_f32 v[120:121], v[114:115], v[180:181]
	v_mul_f32_e32 v115, v123, v123
	v_mul_f32_e32 v114, v121, v121
	v_fmac_f32_e32 v114, v120, v120
	v_fmac_f32_e32 v115, v122, v122
	v_cndmask_b32_e32 v118, v151, v118, vcc
	v_add_f32_e32 v114, v114, v115
	v_lshlrev_b32_e32 v118, 2, v118
	v_add_f32_e32 v114, v124, v114
	ds_bpermute_b32 v115, v118, v114
	v_cmp_lt_i32_e32 vcc, v160, v119
	global_store_dwordx4 v[164:165], v[120:123], off offset:576 nt
	s_waitcnt lgkmcnt(0)
	v_add_f32_e32 v114, v114, v115
	v_cndmask_b32_e32 v116, v151, v160, vcc
	v_lshlrev_b32_e32 v116, 2, v116
	ds_bpermute_b32 v115, v116, v114
	v_cmp_eq_u32_e32 vcc, 0, v166
	v_cvt_pk_bf16_f32 v120, v120, v121
	v_cvt_pk_bf16_f32 v121, v122, v123
	global_store_dwordx2 v[162:163], v[120:121], off offset:288
	s_and_saveexec_b64 s[24:25], vcc
	s_cbranch_execz .LBB0_1860
	s_waitcnt lgkmcnt(0)
	v_add_f32_e32 v117, v114, v115
	s_lshl_b32 s26, s4, 2
	v_lshlrev_b64 v[114:115], 7, v[144:145]
	s_ashr_i32 s27, s26, 31
	v_lshl_add_u64 v[114:115], s[10:11], 0, v[114:115]
	v_lshl_add_u64 v[114:115], s[26:27], 2, v[114:115]
	s_lshl_b32 s6, s41, 2
	v_lshl_add_u64 v[114:115], v[114:115], 0, s[6:7]
	global_store_dword v[114:115], v117, off
.LBB0_1860:
	s_or_b64 exec, exec, s[24:25]
	s_mov_b32 s98, 0x60000
	s_mov_b32 s99, 0
	v_lshl_add_u64 v[216:217], v[218:219], 0, s[98:99]
	global_load_dwordx4 v[168:171], v[216:217], off nt
	global_load_dwordx4 v[172:175], v[216:217], off offset:64 nt
	global_load_dwordx4 v[176:179], v[216:217], off offset:512 nt
	global_load_dwordx4 v[180:183], v[216:217], off offset:576 nt
	v_add_u32_e32 v114, 16, v144
	s_waitcnt lgkmcnt(0)
	v_ashrrev_i32_e32 v115, 31, v114
	v_lshlrev_b64 v[120:121], 11, v[114:115]
	v_lshl_add_u64 v[124:125], v[120:121], 0, v[142:143]
	v_readlane_b32 s52, v254, 7
	v_lshlrev_b64 v[126:127], 2, v[124:125]
	v_readlane_b32 s53, v254, 8
	v_readlane_b32 s54, v254, 9
	v_readlane_b32 s55, v254, 10
	v_lshl_add_u64 v[128:129], s[52:53], 0, v[126:127]
	v_readlane_b32 s56, v254, 11
	v_readlane_b32 s57, v254, 12
	v_readlane_b32 s58, v254, 13
	v_readlane_b32 s59, v254, 14
	v_readlane_b32 s60, v254, 15
	v_readlane_b32 s61, v254, 16
	v_readlane_b32 s62, v254, 17
	v_readlane_b32 s63, v254, 18
	v_readlane_b32 s64, v254, 19
	v_readlane_b32 s65, v254, 20
	v_readlane_b32 s66, v254, 21
	v_readlane_b32 s67, v254, 22
	v_readlane_b32 s52, v254, 32
	v_readlane_b32 s66, v254, 46
	v_readlane_b32 s67, v254, 47
	v_lshl_add_u64 v[124:125], v[124:125], 1, s[88:89]
	v_readlane_b32 s53, v254, 33
	v_lshl_add_u64 v[126:127], s[66:67], 0, v[126:127]
	v_readlane_b32 s54, v254, 34
	v_readlane_b32 s55, v254, 35
	v_readlane_b32 s56, v254, 36
	v_readlane_b32 s57, v254, 37
	v_readlane_b32 s58, v254, 38
	v_readlane_b32 s59, v254, 39
	v_readlane_b32 s60, v254, 40
	v_readlane_b32 s61, v254, 41
	v_readlane_b32 s62, v254, 42
	v_readlane_b32 s63, v254, 43
	v_readlane_b32 s64, v254, 44
	v_readlane_b32 s65, v254, 45
	s_waitcnt vmcnt(19)
	v_pk_add_f32 v[112:113], v[112:113], v[186:187]
	v_pk_add_f32 v[110:111], v[110:111], v[184:185]
	v_cvt_pk_bf16_f32 v185, v112, v113
	v_cvt_pk_bf16_f32 v184, v110, v111
	global_store_dwordx4 v[126:127], v[110:113], off nt
	global_store_dwordx2 v[124:125], v[184:185], off
	v_mul_f32_e32 v111, v111, v111
	v_mul_f32_e32 v113, v113, v113
	v_fmac_f32_e32 v111, v110, v110
	v_fmac_f32_e32 v113, v112, v112
	v_add_f32_e32 v110, v111, v113
	s_waitcnt vmcnt(20)
	v_pk_add_f32 v[108:109], v[108:109], v[190:191]
	v_pk_add_f32 v[106:107], v[106:107], v[188:189]
	v_cvt_pk_bf16_f32 v189, v108, v109
	v_cvt_pk_bf16_f32 v188, v106, v107
	global_store_dwordx4 v[126:127], v[106:109], off offset:64 nt
	global_store_dwordx2 v[124:125], v[188:189], off offset:32
	v_mul_f32_e32 v107, v107, v107
	v_mul_f32_e32 v109, v109, v109
	v_fmac_f32_e32 v107, v106, v106
	v_fmac_f32_e32 v109, v108, v108
	v_add_f32_e32 v106, v107, v109
	v_add_f32_e32 v106, v110, v106
	s_waitcnt vmcnt(21)
	v_pk_add_f32 v[104:105], v[104:105], v[194:195]
	v_pk_add_f32 v[102:103], v[102:103], v[192:193]
	v_cvt_pk_bf16_f32 v193, v104, v105
	v_cvt_pk_bf16_f32 v192, v102, v103
	global_store_dwordx4 v[126:127], v[102:105], off offset:512 nt
	global_store_dwordx2 v[124:125], v[192:193], off offset:256
	v_mul_f32_e32 v103, v103, v103
	v_mul_f32_e32 v105, v105, v105
	v_fmac_f32_e32 v103, v102, v102
	v_fmac_f32_e32 v105, v104, v104
	v_add_f32_e32 v102, v103, v105
	v_add_f32_e32 v104, v106, v102
	s_waitcnt vmcnt(22)
	v_pk_add_f32 v[102:103], v[100:101], v[198:199]
	v_pk_add_f32 v[100:101], v[98:99], v[196:197]
	v_mul_f32_e32 v99, v103, v103
	v_mul_f32_e32 v98, v101, v101
	v_fmac_f32_e32 v98, v100, v100
	v_fmac_f32_e32 v99, v102, v102
	v_add_f32_e32 v98, v98, v99
	v_add_f32_e32 v98, v104, v98
	ds_bpermute_b32 v99, v118, v98
	global_store_dwordx4 v[126:127], v[100:103], off offset:576 nt
	s_waitcnt lgkmcnt(0)
	v_add_f32_e32 v98, v98, v99
	ds_bpermute_b32 v99, v116, v98
	v_cvt_pk_bf16_f32 v100, v100, v101
	v_cvt_pk_bf16_f32 v101, v102, v103
	global_store_dwordx2 v[124:125], v[100:101], off offset:288
	s_and_saveexec_b64 s[24:25], vcc
	s_cbranch_execz .LBB0_1862
	s_waitcnt lgkmcnt(0)
	v_add_f32_e32 v100, v98, v99
	s_lshl_b32 s26, s4, 2
	v_lshlrev_b64 v[98:99], 7, v[114:115]
	s_ashr_i32 s27, s26, 31
	v_lshl_add_u64 v[98:99], s[10:11], 0, v[98:99]
	v_lshl_add_u64 v[98:99], s[26:27], 2, v[98:99]
	s_lshl_b32 s6, s41, 2
	v_lshl_add_u64 v[98:99], v[98:99], 0, s[6:7]
	global_store_dword v[98:99], v100, off
.LBB0_1862:
	s_or_b64 exec, exec, s[24:25]
	s_mov_b32 s98, 0x100000
	s_mov_b32 s99, 0
	v_lshl_add_u64 v[216:217], v[218:219], 0, s[98:99]
	global_load_dwordx4 v[184:187], v[216:217], off nt
	global_load_dwordx4 v[188:191], v[216:217], off offset:64 nt
	global_load_dwordx4 v[192:195], v[216:217], off offset:512 nt
	global_load_dwordx4 v[196:199], v[216:217], off offset:576 nt
	v_add_u32_e32 v98, 32, v144
	s_waitcnt lgkmcnt(0)
	v_ashrrev_i32_e32 v99, 31, v98
	v_lshlrev_b64 v[100:101], 11, v[98:99]
	v_lshl_add_u64 v[104:105], v[100:101], 0, v[142:143]
	v_readlane_b32 s52, v254, 7
	v_lshlrev_b64 v[106:107], 2, v[104:105]
	v_readlane_b32 s53, v254, 8
	v_readlane_b32 s54, v254, 9
	v_readlane_b32 s55, v254, 10
	v_lshl_add_u64 v[108:109], s[52:53], 0, v[106:107]
	v_readlane_b32 s56, v254, 11
	v_readlane_b32 s57, v254, 12
	v_readlane_b32 s58, v254, 13
	v_readlane_b32 s59, v254, 14
	v_readlane_b32 s60, v254, 15
	v_readlane_b32 s61, v254, 16
	v_readlane_b32 s62, v254, 17
	v_readlane_b32 s63, v254, 18
	v_readlane_b32 s64, v254, 19
	v_readlane_b32 s65, v254, 20
	v_readlane_b32 s66, v254, 21
	v_readlane_b32 s67, v254, 22
	v_readlane_b32 s52, v254, 32
	v_readlane_b32 s66, v254, 46
	v_readlane_b32 s67, v254, 47
	v_lshl_add_u64 v[104:105], v[104:105], 1, s[88:89]
	v_readlane_b32 s53, v254, 33
	v_lshl_add_u64 v[106:107], s[66:67], 0, v[106:107]
	v_readlane_b32 s54, v254, 34
	v_readlane_b32 s55, v254, 35
	v_readlane_b32 s56, v254, 36
	v_readlane_b32 s57, v254, 37
	v_readlane_b32 s58, v254, 38
	v_readlane_b32 s59, v254, 39
	v_readlane_b32 s60, v254, 40
	v_readlane_b32 s61, v254, 41
	v_readlane_b32 s62, v254, 42
	v_readlane_b32 s63, v254, 43
	v_readlane_b32 s64, v254, 44
	v_readlane_b32 s65, v254, 45
	s_waitcnt vmcnt(27)
	v_pk_add_f32 v[96:97], v[96:97], v[202:203]
	v_pk_add_f32 v[94:95], v[94:95], v[200:201]
	v_cvt_pk_bf16_f32 v201, v96, v97
	v_cvt_pk_bf16_f32 v200, v94, v95
	global_store_dwordx4 v[106:107], v[94:97], off nt
	global_store_dwordx2 v[104:105], v[200:201], off
	v_mul_f32_e32 v95, v95, v95
	v_mul_f32_e32 v97, v97, v97
	v_fmac_f32_e32 v95, v94, v94
	v_fmac_f32_e32 v97, v96, v96
	v_add_f32_e32 v94, v95, v97
	s_waitcnt vmcnt(28)
	v_pk_add_f32 v[92:93], v[92:93], v[206:207]
	v_pk_add_f32 v[90:91], v[90:91], v[204:205]
	v_cvt_pk_bf16_f32 v205, v92, v93
	v_cvt_pk_bf16_f32 v204, v90, v91
	global_store_dwordx4 v[106:107], v[90:93], off offset:64 nt
	global_store_dwordx2 v[104:105], v[204:205], off offset:32
	v_mul_f32_e32 v91, v91, v91
	v_mul_f32_e32 v93, v93, v93
	v_fmac_f32_e32 v91, v90, v90
	v_fmac_f32_e32 v93, v92, v92
	v_add_f32_e32 v90, v91, v93
	v_add_f32_e32 v90, v94, v90
	s_waitcnt vmcnt(29)
	v_pk_add_f32 v[88:89], v[88:89], v[210:211]
	v_pk_add_f32 v[86:87], v[86:87], v[208:209]
	v_cvt_pk_bf16_f32 v209, v88, v89
	v_cvt_pk_bf16_f32 v208, v86, v87
	global_store_dwordx4 v[106:107], v[86:89], off offset:512 nt
	global_store_dwordx2 v[104:105], v[208:209], off offset:256
	v_mul_f32_e32 v87, v87, v87
	v_mul_f32_e32 v89, v89, v89
	v_fmac_f32_e32 v87, v86, v86
	v_fmac_f32_e32 v89, v88, v88
	v_add_f32_e32 v86, v87, v89
	v_add_f32_e32 v88, v90, v86
	s_waitcnt vmcnt(30)
	v_pk_add_f32 v[86:87], v[84:85], v[214:215]
	v_pk_add_f32 v[84:85], v[82:83], v[212:213]
	v_mul_f32_e32 v83, v87, v87
	v_mul_f32_e32 v82, v85, v85
	v_fmac_f32_e32 v82, v84, v84
	v_fmac_f32_e32 v83, v86, v86
	v_add_f32_e32 v82, v82, v83
	v_add_f32_e32 v82, v88, v82
	ds_bpermute_b32 v83, v118, v82
	global_store_dwordx4 v[106:107], v[84:87], off offset:576 nt
	s_waitcnt lgkmcnt(0)
	v_add_f32_e32 v82, v82, v83
	ds_bpermute_b32 v83, v116, v82
	v_cvt_pk_bf16_f32 v84, v84, v85
	v_cvt_pk_bf16_f32 v85, v86, v87
	global_store_dwordx2 v[104:105], v[84:85], off offset:288
	s_and_saveexec_b64 s[24:25], vcc
	s_cbranch_execz .LBB0_1864
	s_waitcnt lgkmcnt(0)
	v_add_f32_e32 v84, v82, v83
	s_lshl_b32 s26, s4, 2
	v_lshlrev_b64 v[82:83], 7, v[98:99]
	s_ashr_i32 s27, s26, 31
	v_lshl_add_u64 v[82:83], s[10:11], 0, v[82:83]
	v_lshl_add_u64 v[82:83], s[26:27], 2, v[82:83]
	s_lshl_b32 s6, s41, 2
	v_lshl_add_u64 v[82:83], v[82:83], 0, s[6:7]
	global_store_dword v[82:83], v84, off
.LBB0_1864:
	s_or_b64 exec, exec, s[24:25]
	s_mov_b32 s98, 0x120000
	s_mov_b32 s99, 0
	v_lshl_add_u64 v[216:217], v[218:219], 0, s[98:99]
	global_load_dwordx4 v[200:203], v[216:217], off nt
	global_load_dwordx4 v[204:207], v[216:217], off offset:64 nt
	global_load_dwordx4 v[208:211], v[216:217], off offset:512 nt
	global_load_dwordx4 v[212:215], v[216:217], off offset:576 nt
	v_add_u32_e32 v82, 48, v144
	s_waitcnt lgkmcnt(0)
	v_ashrrev_i32_e32 v83, 31, v82
	v_lshlrev_b64 v[84:85], 11, v[82:83]
	v_lshl_add_u64 v[88:89], v[84:85], 0, v[142:143]
	v_readlane_b32 s52, v254, 7
	v_lshlrev_b64 v[90:91], 2, v[88:89]
	v_readlane_b32 s53, v254, 8
	v_readlane_b32 s54, v254, 9
	v_readlane_b32 s55, v254, 10
	v_lshl_add_u64 v[92:93], s[52:53], 0, v[90:91]
	v_readlane_b32 s56, v254, 11
	v_readlane_b32 s57, v254, 12
	v_readlane_b32 s58, v254, 13
	v_readlane_b32 s59, v254, 14
	v_readlane_b32 s60, v254, 15
	v_readlane_b32 s61, v254, 16
	v_readlane_b32 s62, v254, 17
	v_readlane_b32 s63, v254, 18
	v_readlane_b32 s64, v254, 19
	v_readlane_b32 s65, v254, 20
	v_readlane_b32 s66, v254, 21
	v_readlane_b32 s67, v254, 22
	v_readlane_b32 s52, v254, 32
	v_readlane_b32 s66, v254, 46
	v_readlane_b32 s67, v254, 47
	v_lshl_add_u64 v[88:89], v[88:89], 1, s[88:89]
	v_readlane_b32 s53, v254, 33
	v_lshl_add_u64 v[90:91], s[66:67], 0, v[90:91]
	v_readlane_b32 s54, v254, 34
	v_readlane_b32 s55, v254, 35
	v_readlane_b32 s56, v254, 36
	v_readlane_b32 s57, v254, 37
	v_readlane_b32 s58, v254, 38
	v_readlane_b32 s59, v254, 39
	v_readlane_b32 s60, v254, 40
	v_readlane_b32 s61, v254, 41
	v_readlane_b32 s62, v254, 42
	v_readlane_b32 s63, v254, 43
	v_readlane_b32 s64, v254, 44
	v_readlane_b32 s65, v254, 45
	s_waitcnt vmcnt(27)
	v_pk_add_f32 v[80:81], v[80:81], v[170:171]
	v_pk_add_f32 v[78:79], v[78:79], v[168:169]
	v_cvt_pk_bf16_f32 v169, v80, v81
	v_cvt_pk_bf16_f32 v168, v78, v79
	global_store_dwordx4 v[90:91], v[78:81], off nt
	global_store_dwordx2 v[88:89], v[168:169], off
	v_mul_f32_e32 v79, v79, v79
	v_mul_f32_e32 v81, v81, v81
	v_fmac_f32_e32 v79, v78, v78
	v_fmac_f32_e32 v81, v80, v80
	v_add_f32_e32 v78, v79, v81
	s_waitcnt vmcnt(28)
	v_pk_add_f32 v[76:77], v[76:77], v[174:175]
	v_pk_add_f32 v[74:75], v[74:75], v[172:173]
	v_cvt_pk_bf16_f32 v173, v76, v77
	v_cvt_pk_bf16_f32 v172, v74, v75
	global_store_dwordx4 v[90:91], v[74:77], off offset:64 nt
	global_store_dwordx2 v[88:89], v[172:173], off offset:32
	v_mul_f32_e32 v75, v75, v75
	v_mul_f32_e32 v77, v77, v77
	v_fmac_f32_e32 v75, v74, v74
	v_fmac_f32_e32 v77, v76, v76
	v_add_f32_e32 v74, v75, v77
	v_add_f32_e32 v74, v78, v74
	s_waitcnt vmcnt(29)
	v_pk_add_f32 v[72:73], v[72:73], v[178:179]
	v_pk_add_f32 v[70:71], v[70:71], v[176:177]
	v_cvt_pk_bf16_f32 v177, v72, v73
	v_cvt_pk_bf16_f32 v176, v70, v71
	global_store_dwordx4 v[90:91], v[70:73], off offset:512 nt
	global_store_dwordx2 v[88:89], v[176:177], off offset:256
	v_mul_f32_e32 v71, v71, v71
	v_mul_f32_e32 v73, v73, v73
	v_fmac_f32_e32 v71, v70, v70
	v_fmac_f32_e32 v73, v72, v72
	v_add_f32_e32 v70, v71, v73
	v_add_f32_e32 v72, v74, v70
	s_waitcnt vmcnt(30)
	v_pk_add_f32 v[70:71], v[68:69], v[182:183]
	v_pk_add_f32 v[68:69], v[66:67], v[180:181]
	v_mul_f32_e32 v67, v71, v71
	v_mul_f32_e32 v66, v69, v69
	v_fmac_f32_e32 v66, v68, v68
	v_fmac_f32_e32 v67, v70, v70
	v_add_f32_e32 v66, v66, v67
	v_add_f32_e32 v66, v72, v66
	ds_bpermute_b32 v67, v118, v66
	global_store_dwordx4 v[90:91], v[68:71], off offset:576 nt
	s_waitcnt lgkmcnt(0)
	v_add_f32_e32 v66, v66, v67
	ds_bpermute_b32 v67, v116, v66
	v_cvt_pk_bf16_f32 v68, v68, v69
	v_cvt_pk_bf16_f32 v69, v70, v71
	global_store_dwordx2 v[88:89], v[68:69], off offset:288
	s_and_saveexec_b64 s[24:25], vcc
	s_cbranch_execz .LBB0_1866
	s_waitcnt lgkmcnt(0)
	v_add_f32_e32 v68, v66, v67
	s_lshl_b32 s26, s4, 2
	v_lshlrev_b64 v[66:67], 7, v[82:83]
	s_ashr_i32 s27, s26, 31
	v_lshl_add_u64 v[66:67], s[10:11], 0, v[66:67]
	v_lshl_add_u64 v[66:67], s[26:27], 2, v[66:67]
	s_lshl_b32 s6, s41, 2
	v_lshl_add_u64 v[66:67], v[66:67], 0, s[6:7]
	global_store_dword v[66:67], v68, off
.LBB0_1866:
	s_or_b64 exec, exec, s[24:25]
	s_mov_b32 s98, 0x140000
	s_mov_b32 s99, 0
	v_lshl_add_u64 v[216:217], v[218:219], 0, s[98:99]
	global_load_dwordx4 v[168:171], v[216:217], off nt
	global_load_dwordx4 v[172:175], v[216:217], off offset:64 nt
	global_load_dwordx4 v[176:179], v[216:217], off offset:512 nt
	global_load_dwordx4 v[180:183], v[216:217], off offset:576 nt
	v_add_u32_e32 v66, 0x80, v144
	s_waitcnt lgkmcnt(0)
	v_ashrrev_i32_e32 v67, 31, v66
	v_lshlrev_b64 v[68:69], 11, v[66:67]
	v_lshl_add_u64 v[72:73], v[68:69], 0, v[142:143]
	v_readlane_b32 s52, v254, 7
	v_lshlrev_b64 v[74:75], 2, v[72:73]
	v_readlane_b32 s53, v254, 8
	v_readlane_b32 s54, v254, 9
	v_readlane_b32 s55, v254, 10
	v_lshl_add_u64 v[76:77], s[52:53], 0, v[74:75]
	v_readlane_b32 s56, v254, 11
	v_readlane_b32 s57, v254, 12
	v_readlane_b32 s58, v254, 13
	v_readlane_b32 s59, v254, 14
	v_readlane_b32 s60, v254, 15
	v_readlane_b32 s61, v254, 16
	v_readlane_b32 s62, v254, 17
	v_readlane_b32 s63, v254, 18
	v_readlane_b32 s64, v254, 19
	v_readlane_b32 s65, v254, 20
	v_readlane_b32 s66, v254, 21
	v_readlane_b32 s67, v254, 22
	v_readlane_b32 s52, v254, 32
	v_readlane_b32 s66, v254, 46
	v_readlane_b32 s67, v254, 47
	v_lshl_add_u64 v[72:73], v[72:73], 1, s[88:89]
	v_readlane_b32 s53, v254, 33
	v_lshl_add_u64 v[74:75], s[66:67], 0, v[74:75]
	v_readlane_b32 s54, v254, 34
	v_readlane_b32 s55, v254, 35
	v_readlane_b32 s56, v254, 36
	v_readlane_b32 s57, v254, 37
	v_readlane_b32 s58, v254, 38
	v_readlane_b32 s59, v254, 39
	v_readlane_b32 s60, v254, 40
	v_readlane_b32 s61, v254, 41
	v_readlane_b32 s62, v254, 42
	v_readlane_b32 s63, v254, 43
	v_readlane_b32 s64, v254, 44
	v_readlane_b32 s65, v254, 45
	s_waitcnt vmcnt(27)
	v_pk_add_f32 v[64:65], v[64:65], v[186:187]
	v_pk_add_f32 v[62:63], v[62:63], v[184:185]
	v_cvt_pk_bf16_f32 v185, v64, v65
	v_cvt_pk_bf16_f32 v184, v62, v63
	global_store_dwordx4 v[74:75], v[62:65], off nt
	global_store_dwordx2 v[72:73], v[184:185], off
	v_mul_f32_e32 v63, v63, v63
	v_mul_f32_e32 v65, v65, v65
	v_fmac_f32_e32 v63, v62, v62
	v_fmac_f32_e32 v65, v64, v64
	v_add_f32_e32 v62, v63, v65
	s_waitcnt vmcnt(28)
	v_pk_add_f32 v[60:61], v[60:61], v[190:191]
	v_pk_add_f32 v[58:59], v[58:59], v[188:189]
	v_cvt_pk_bf16_f32 v189, v60, v61
	v_cvt_pk_bf16_f32 v188, v58, v59
	global_store_dwordx4 v[74:75], v[58:61], off offset:64 nt
	global_store_dwordx2 v[72:73], v[188:189], off offset:32
	v_mul_f32_e32 v59, v59, v59
	v_mul_f32_e32 v61, v61, v61
	v_fmac_f32_e32 v59, v58, v58
	v_fmac_f32_e32 v61, v60, v60
	v_add_f32_e32 v58, v59, v61
	v_add_f32_e32 v58, v62, v58
	s_waitcnt vmcnt(29)
	v_pk_add_f32 v[56:57], v[56:57], v[194:195]
	v_pk_add_f32 v[54:55], v[54:55], v[192:193]
	v_cvt_pk_bf16_f32 v193, v56, v57
	v_cvt_pk_bf16_f32 v192, v54, v55
	global_store_dwordx4 v[74:75], v[54:57], off offset:512 nt
	global_store_dwordx2 v[72:73], v[192:193], off offset:256
	v_mul_f32_e32 v55, v55, v55
	v_mul_f32_e32 v57, v57, v57
	v_fmac_f32_e32 v55, v54, v54
	v_fmac_f32_e32 v57, v56, v56
	v_add_f32_e32 v54, v55, v57
	v_add_f32_e32 v56, v58, v54
	s_waitcnt vmcnt(30)
	v_pk_add_f32 v[54:55], v[52:53], v[198:199]
	v_pk_add_f32 v[52:53], v[50:51], v[196:197]
	v_mul_f32_e32 v51, v55, v55
	v_mul_f32_e32 v50, v53, v53
	v_fmac_f32_e32 v50, v52, v52
	v_fmac_f32_e32 v51, v54, v54
	v_add_f32_e32 v50, v50, v51
	v_add_f32_e32 v50, v56, v50
	ds_bpermute_b32 v51, v118, v50
	global_store_dwordx4 v[74:75], v[52:55], off offset:576 nt
	s_waitcnt lgkmcnt(0)
	v_add_f32_e32 v50, v50, v51
	ds_bpermute_b32 v51, v116, v50
	v_cvt_pk_bf16_f32 v52, v52, v53
	v_cvt_pk_bf16_f32 v53, v54, v55
	global_store_dwordx2 v[72:73], v[52:53], off offset:288
	s_and_saveexec_b64 s[24:25], vcc
	s_cbranch_execz .LBB0_1868
	s_waitcnt lgkmcnt(0)
	v_add_f32_e32 v52, v50, v51
	s_lshl_b32 s26, s4, 2
	v_lshlrev_b64 v[50:51], 7, v[66:67]
	s_ashr_i32 s27, s26, 31
	v_lshl_add_u64 v[50:51], s[10:11], 0, v[50:51]
	v_lshl_add_u64 v[50:51], s[26:27], 2, v[50:51]
	s_lshl_b32 s6, s41, 2
	v_lshl_add_u64 v[50:51], v[50:51], 0, s[6:7]
	global_store_dword v[50:51], v52, off
.LBB0_1868:
	s_or_b64 exec, exec, s[24:25]
	s_mov_b32 s98, 0x160000
	s_mov_b32 s99, 0
	v_lshl_add_u64 v[216:217], v[218:219], 0, s[98:99]
	global_load_dwordx4 v[184:187], v[216:217], off nt
	global_load_dwordx4 v[188:191], v[216:217], off offset:64 nt
	global_load_dwordx4 v[192:195], v[216:217], off offset:512 nt
	global_load_dwordx4 v[196:199], v[216:217], off offset:576 nt
	v_add_u32_e32 v50, 0x90, v144
	s_waitcnt lgkmcnt(0)
	v_ashrrev_i32_e32 v51, 31, v50
	v_lshlrev_b64 v[52:53], 11, v[50:51]
	v_lshl_add_u64 v[56:57], v[52:53], 0, v[142:143]
	v_readlane_b32 s52, v254, 7
	v_lshlrev_b64 v[58:59], 2, v[56:57]
	v_readlane_b32 s53, v254, 8
	v_readlane_b32 s54, v254, 9
	v_readlane_b32 s55, v254, 10
	v_lshl_add_u64 v[60:61], s[52:53], 0, v[58:59]
	v_readlane_b32 s56, v254, 11
	v_readlane_b32 s57, v254, 12
	v_readlane_b32 s58, v254, 13
	v_readlane_b32 s59, v254, 14
	v_readlane_b32 s60, v254, 15
	v_readlane_b32 s61, v254, 16
	v_readlane_b32 s62, v254, 17
	v_readlane_b32 s63, v254, 18
	v_readlane_b32 s64, v254, 19
	v_readlane_b32 s65, v254, 20
	v_readlane_b32 s66, v254, 21
	v_readlane_b32 s67, v254, 22
	v_readlane_b32 s52, v254, 32
	v_readlane_b32 s66, v254, 46
	v_readlane_b32 s67, v254, 47
	v_lshl_add_u64 v[56:57], v[56:57], 1, s[88:89]
	v_readlane_b32 s53, v254, 33
	v_lshl_add_u64 v[58:59], s[66:67], 0, v[58:59]
	v_readlane_b32 s54, v254, 34
	v_readlane_b32 s55, v254, 35
	v_readlane_b32 s56, v254, 36
	v_readlane_b32 s57, v254, 37
	v_readlane_b32 s58, v254, 38
	v_readlane_b32 s59, v254, 39
	v_readlane_b32 s60, v254, 40
	v_readlane_b32 s61, v254, 41
	v_readlane_b32 s62, v254, 42
	v_readlane_b32 s63, v254, 43
	v_readlane_b32 s64, v254, 44
	v_readlane_b32 s65, v254, 45
	s_waitcnt vmcnt(27)
	v_pk_add_f32 v[48:49], v[48:49], v[202:203]
	v_pk_add_f32 v[46:47], v[46:47], v[200:201]
	v_cvt_pk_bf16_f32 v201, v48, v49
	v_cvt_pk_bf16_f32 v200, v46, v47
	global_store_dwordx4 v[58:59], v[46:49], off nt
	global_store_dwordx2 v[56:57], v[200:201], off
	v_mul_f32_e32 v47, v47, v47
	v_mul_f32_e32 v49, v49, v49
	v_fmac_f32_e32 v47, v46, v46
	v_fmac_f32_e32 v49, v48, v48
	v_add_f32_e32 v46, v47, v49
	s_waitcnt vmcnt(28)
	v_pk_add_f32 v[44:45], v[44:45], v[206:207]
	v_pk_add_f32 v[42:43], v[42:43], v[204:205]
	v_cvt_pk_bf16_f32 v205, v44, v45
	v_cvt_pk_bf16_f32 v204, v42, v43
	global_store_dwordx4 v[58:59], v[42:45], off offset:64 nt
	global_store_dwordx2 v[56:57], v[204:205], off offset:32
	v_mul_f32_e32 v43, v43, v43
	v_mul_f32_e32 v45, v45, v45
	v_fmac_f32_e32 v43, v42, v42
	v_fmac_f32_e32 v45, v44, v44
	v_add_f32_e32 v42, v43, v45
	v_add_f32_e32 v42, v46, v42
	s_waitcnt vmcnt(29)
	v_pk_add_f32 v[40:41], v[40:41], v[210:211]
	v_pk_add_f32 v[38:39], v[38:39], v[208:209]
	v_cvt_pk_bf16_f32 v209, v40, v41
	v_cvt_pk_bf16_f32 v208, v38, v39
	global_store_dwordx4 v[58:59], v[38:41], off offset:512 nt
	global_store_dwordx2 v[56:57], v[208:209], off offset:256
	v_mul_f32_e32 v39, v39, v39
	v_mul_f32_e32 v41, v41, v41
	v_fmac_f32_e32 v39, v38, v38
	v_fmac_f32_e32 v41, v40, v40
	v_add_f32_e32 v38, v39, v41
	v_add_f32_e32 v40, v42, v38
	s_waitcnt vmcnt(30)
	v_pk_add_f32 v[38:39], v[36:37], v[214:215]
	v_pk_add_f32 v[36:37], v[34:35], v[212:213]
	v_mul_f32_e32 v35, v39, v39
	v_mul_f32_e32 v34, v37, v37
	v_fmac_f32_e32 v34, v36, v36
	v_fmac_f32_e32 v35, v38, v38
	v_add_f32_e32 v34, v34, v35
	v_add_f32_e32 v34, v40, v34
	ds_bpermute_b32 v35, v118, v34
	global_store_dwordx4 v[58:59], v[36:39], off offset:576 nt
	s_waitcnt lgkmcnt(0)
	v_add_f32_e32 v34, v34, v35
	ds_bpermute_b32 v35, v116, v34
	v_cvt_pk_bf16_f32 v36, v36, v37
	v_cvt_pk_bf16_f32 v37, v38, v39
	global_store_dwordx2 v[56:57], v[36:37], off offset:288
	s_and_saveexec_b64 s[24:25], vcc
	s_cbranch_execz .LBB0_1870
	s_waitcnt lgkmcnt(0)
	v_add_f32_e32 v36, v34, v35
	s_lshl_b32 s26, s4, 2
	v_lshlrev_b64 v[34:35], 7, v[50:51]
	s_ashr_i32 s27, s26, 31
	v_lshl_add_u64 v[34:35], s[10:11], 0, v[34:35]
	v_lshl_add_u64 v[34:35], s[26:27], 2, v[34:35]
	s_lshl_b32 s6, s41, 2
	v_lshl_add_u64 v[34:35], v[34:35], 0, s[6:7]
	global_store_dword v[34:35], v36, off
.LBB0_1870:
	s_or_b64 exec, exec, s[24:25]
	v_add_u32_e32 v34, 0xa0, v144
	s_waitcnt lgkmcnt(0)
	v_ashrrev_i32_e32 v35, 31, v34
	v_lshlrev_b64 v[36:37], 11, v[34:35]
	v_lshl_add_u64 v[40:41], v[36:37], 0, v[142:143]
	v_readlane_b32 s52, v254, 7
	v_lshlrev_b64 v[42:43], 2, v[40:41]
	v_readlane_b32 s53, v254, 8
	v_readlane_b32 s54, v254, 9
	v_readlane_b32 s55, v254, 10
	v_lshl_add_u64 v[44:45], s[52:53], 0, v[42:43]
	v_readlane_b32 s56, v254, 11
	v_readlane_b32 s57, v254, 12
	v_readlane_b32 s58, v254, 13
	v_readlane_b32 s59, v254, 14
	v_readlane_b32 s60, v254, 15
	v_readlane_b32 s61, v254, 16
	v_readlane_b32 s62, v254, 17
	v_readlane_b32 s63, v254, 18
	v_readlane_b32 s64, v254, 19
	v_readlane_b32 s65, v254, 20
	v_readlane_b32 s66, v254, 21
	v_readlane_b32 s67, v254, 22
	v_readlane_b32 s52, v254, 32
	v_readlane_b32 s66, v254, 46
	v_readlane_b32 s67, v254, 47
	v_lshl_add_u64 v[40:41], v[40:41], 1, s[88:89]
	v_readlane_b32 s53, v254, 33
	v_lshl_add_u64 v[42:43], s[66:67], 0, v[42:43]
	v_readlane_b32 s54, v254, 34
	v_readlane_b32 s55, v254, 35
	v_readlane_b32 s56, v254, 36
	v_readlane_b32 s57, v254, 37
	v_readlane_b32 s58, v254, 38
	v_readlane_b32 s59, v254, 39
	v_readlane_b32 s60, v254, 40
	v_readlane_b32 s61, v254, 41
	v_readlane_b32 s62, v254, 42
	v_readlane_b32 s63, v254, 43
	v_readlane_b32 s64, v254, 44
	v_readlane_b32 s65, v254, 45
	s_waitcnt vmcnt(23)
	v_pk_add_f32 v[32:33], v[32:33], v[170:171]
	v_pk_add_f32 v[30:31], v[30:31], v[168:169]
	v_cvt_pk_bf16_f32 v169, v32, v33
	v_cvt_pk_bf16_f32 v168, v30, v31
	global_store_dwordx4 v[42:43], v[30:33], off nt
	global_store_dwordx2 v[40:41], v[168:169], off
	v_mul_f32_e32 v31, v31, v31
	v_mul_f32_e32 v33, v33, v33
	v_fmac_f32_e32 v31, v30, v30
	v_fmac_f32_e32 v33, v32, v32
	v_add_f32_e32 v30, v31, v33
	s_waitcnt vmcnt(24)
	v_pk_add_f32 v[28:29], v[28:29], v[174:175]
	v_pk_add_f32 v[26:27], v[26:27], v[172:173]
	v_cvt_pk_bf16_f32 v173, v28, v29
	v_cvt_pk_bf16_f32 v172, v26, v27
	global_store_dwordx4 v[42:43], v[26:29], off offset:64 nt
	global_store_dwordx2 v[40:41], v[172:173], off offset:32
	v_mul_f32_e32 v27, v27, v27
	v_mul_f32_e32 v29, v29, v29
	v_fmac_f32_e32 v27, v26, v26
	v_fmac_f32_e32 v29, v28, v28
	v_add_f32_e32 v26, v27, v29
	v_add_f32_e32 v26, v30, v26
	s_waitcnt vmcnt(25)
	v_pk_add_f32 v[24:25], v[24:25], v[178:179]
	v_pk_add_f32 v[22:23], v[22:23], v[176:177]
	v_cvt_pk_bf16_f32 v177, v24, v25
	v_cvt_pk_bf16_f32 v176, v22, v23
	global_store_dwordx4 v[42:43], v[22:25], off offset:512 nt
	global_store_dwordx2 v[40:41], v[176:177], off offset:256
	v_mul_f32_e32 v23, v23, v23
	v_mul_f32_e32 v25, v25, v25
	v_fmac_f32_e32 v23, v22, v22
	v_fmac_f32_e32 v25, v24, v24
	v_add_f32_e32 v22, v23, v25
	v_add_f32_e32 v24, v26, v22
	s_waitcnt vmcnt(26)
	v_pk_add_f32 v[22:23], v[20:21], v[182:183]
	v_pk_add_f32 v[20:21], v[18:19], v[180:181]
	v_mul_f32_e32 v19, v23, v23
	v_mul_f32_e32 v18, v21, v21
	v_fmac_f32_e32 v18, v20, v20
	v_fmac_f32_e32 v19, v22, v22
	v_add_f32_e32 v18, v18, v19
	v_add_f32_e32 v18, v24, v18
	ds_bpermute_b32 v19, v118, v18
	global_store_dwordx4 v[42:43], v[20:23], off offset:576 nt
	s_waitcnt lgkmcnt(0)
	v_add_f32_e32 v18, v18, v19
	ds_bpermute_b32 v19, v116, v18
	v_cvt_pk_bf16_f32 v20, v20, v21
	v_cvt_pk_bf16_f32 v21, v22, v23
	global_store_dwordx2 v[40:41], v[20:21], off offset:288
	s_and_saveexec_b64 s[24:25], vcc
	s_cbranch_execz .LBB0_1872
	s_waitcnt lgkmcnt(0)
	v_add_f32_e32 v20, v18, v19
	s_lshl_b32 s26, s4, 2
	v_lshlrev_b64 v[18:19], 7, v[34:35]
	s_ashr_i32 s27, s26, 31
	v_lshl_add_u64 v[18:19], s[10:11], 0, v[18:19]
	v_lshl_add_u64 v[18:19], s[26:27], 2, v[18:19]
	s_lshl_b32 s6, s41, 2
	v_lshl_add_u64 v[18:19], v[18:19], 0, s[6:7]
	global_store_dword v[18:19], v20, off
.LBB0_1872:
	s_or_b64 exec, exec, s[24:25]
	v_add_u32_e32 v18, 0xb0, v144
	s_waitcnt lgkmcnt(0)
	v_ashrrev_i32_e32 v19, 31, v18
	v_lshlrev_b64 v[20:21], 11, v[18:19]
	v_lshl_add_u64 v[24:25], v[20:21], 0, v[142:143]
	v_readlane_b32 s52, v254, 7
	v_lshlrev_b64 v[26:27], 2, v[24:25]
	v_readlane_b32 s53, v254, 8
	v_readlane_b32 s54, v254, 9
	v_readlane_b32 s55, v254, 10
	v_lshl_add_u64 v[28:29], s[52:53], 0, v[26:27]
	v_readlane_b32 s56, v254, 11
	v_readlane_b32 s57, v254, 12
	v_readlane_b32 s58, v254, 13
	v_readlane_b32 s59, v254, 14
	v_readlane_b32 s60, v254, 15
	v_readlane_b32 s61, v254, 16
	v_readlane_b32 s62, v254, 17
	v_readlane_b32 s63, v254, 18
	v_readlane_b32 s64, v254, 19
	v_readlane_b32 s65, v254, 20
	v_readlane_b32 s66, v254, 21
	v_readlane_b32 s67, v254, 22
	v_readlane_b32 s52, v254, 32
	v_readlane_b32 s66, v254, 46
	v_readlane_b32 s67, v254, 47
	v_lshl_add_u64 v[24:25], v[24:25], 1, s[88:89]
	v_readlane_b32 s53, v254, 33
	v_lshl_add_u64 v[26:27], s[66:67], 0, v[26:27]
	v_readlane_b32 s54, v254, 34
	v_readlane_b32 s55, v254, 35
	v_readlane_b32 s56, v254, 36
	v_readlane_b32 s57, v254, 37
	v_readlane_b32 s58, v254, 38
	v_readlane_b32 s59, v254, 39
	v_readlane_b32 s60, v254, 40
	v_readlane_b32 s61, v254, 41
	v_readlane_b32 s62, v254, 42
	v_readlane_b32 s63, v254, 43
	v_readlane_b32 s64, v254, 44
	v_readlane_b32 s65, v254, 45
	s_waitcnt vmcnt(19)
	v_pk_add_f32 v[16:17], v[16:17], v[186:187]
	v_pk_add_f32 v[14:15], v[14:15], v[184:185]
	v_cvt_pk_bf16_f32 v185, v16, v17
	v_cvt_pk_bf16_f32 v184, v14, v15
	global_store_dwordx4 v[26:27], v[14:17], off nt
	global_store_dwordx2 v[24:25], v[184:185], off
	v_mul_f32_e32 v15, v15, v15
	v_mul_f32_e32 v17, v17, v17
	v_fmac_f32_e32 v15, v14, v14
	v_fmac_f32_e32 v17, v16, v16
	v_add_f32_e32 v14, v15, v17
	s_waitcnt vmcnt(20)
	v_pk_add_f32 v[12:13], v[12:13], v[190:191]
	v_pk_add_f32 v[10:11], v[10:11], v[188:189]
	v_cvt_pk_bf16_f32 v189, v12, v13
	v_cvt_pk_bf16_f32 v188, v10, v11
	global_store_dwordx4 v[26:27], v[10:13], off offset:64 nt
	global_store_dwordx2 v[24:25], v[188:189], off offset:32
	v_mul_f32_e32 v11, v11, v11
	v_mul_f32_e32 v13, v13, v13
	v_fmac_f32_e32 v11, v10, v10
	v_fmac_f32_e32 v13, v12, v12
	v_add_f32_e32 v10, v11, v13
	v_add_f32_e32 v10, v14, v10
	s_waitcnt vmcnt(21)
	v_pk_add_f32 v[8:9], v[8:9], v[194:195]
	v_pk_add_f32 v[6:7], v[6:7], v[192:193]
	v_cvt_pk_bf16_f32 v193, v8, v9
	v_cvt_pk_bf16_f32 v192, v6, v7
	global_store_dwordx4 v[26:27], v[6:9], off offset:512 nt
	global_store_dwordx2 v[24:25], v[192:193], off offset:256
	v_mul_f32_e32 v7, v7, v7
	v_mul_f32_e32 v9, v9, v9
	v_fmac_f32_e32 v7, v6, v6
	v_fmac_f32_e32 v9, v8, v8
	v_add_f32_e32 v6, v7, v9
	v_add_f32_e32 v8, v10, v6
	s_waitcnt vmcnt(22)
	v_pk_add_f32 v[6:7], v[4:5], v[198:199]
	v_pk_add_f32 v[4:5], v[2:3], v[196:197]
	v_mul_f32_e32 v3, v7, v7
	v_mul_f32_e32 v2, v5, v5
	v_fmac_f32_e32 v2, v4, v4
	v_fmac_f32_e32 v3, v6, v6
	v_add_f32_e32 v2, v2, v3
	v_add_f32_e32 v2, v8, v2
	ds_bpermute_b32 v3, v118, v2
	global_store_dwordx4 v[26:27], v[4:7], off offset:576 nt
	s_waitcnt lgkmcnt(0)
	v_add_f32_e32 v2, v2, v3
	ds_bpermute_b32 v3, v116, v2
	v_cvt_pk_bf16_f32 v4, v4, v5
	v_cvt_pk_bf16_f32 v5, v6, v7
	global_store_dwordx2 v[24:25], v[4:5], off offset:288
	s_and_saveexec_b64 s[24:25], vcc
	s_cbranch_execz .LBB0_1874
	s_waitcnt lgkmcnt(0)
	v_add_f32_e32 v4, v2, v3
	s_lshl_b32 s26, s4, 2
	v_lshlrev_b64 v[2:3], 7, v[18:19]
	s_ashr_i32 s27, s26, 31
	v_lshl_add_u64 v[2:3], s[10:11], 0, v[2:3]
	v_lshl_add_u64 v[2:3], s[26:27], 2, v[2:3]
	s_lshl_b32 s6, s41, 2
	v_lshl_add_u64 v[2:3], v[2:3], 0, s[6:7]
	global_store_dword v[2:3], v4, off

.LBB0_2121:
	s_lshl_b32 s4, s4, 8
	v_mov_b32_e32 v143, v146
	v_mov_b32_e32 v164, v1
	s_lshl_b32 s18, s28, 8
	s_add_i32 s4, s4, s36
	s_or_b32 s18, s18, s37
	v_add_u32_e32 v144, s4, v143
	v_lshl_add_u32 v142, v164, 2, s18
	v_ashrrev_i32_e32 v145, 31, v144
	v_ashrrev_i32_e32 v143, 31, v142
	v_lshlrev_b64 v[152:153], 11, v[144:145]
	v_readlane_b32 s48, v254, 32
	v_lshl_add_u64 v[156:157], v[152:153], 0, v[142:143]
	v_readlane_b32 s62, v254, 46
	v_readlane_b32 s63, v254, 47
	v_lshl_add_u64 v[162:163], v[156:157], 1, s[88:89]
	v_xor_b32_e32 v165, 32, v151
	v_lshl_add_u64 v[160:161], v[156:157], 2, s[62:63]
	v_mov_b32_e32 v216, v160
	v_mov_b32_e32 v217, v161
	global_load_dwordx4 v[166:169], v[216:217], off nt
	global_load_dwordx4 v[170:173], v[216:217], off offset:64 nt
	global_load_dwordx4 v[174:177], v[216:217], off offset:512 nt
	global_load_dwordx4 v[178:181], v[216:217], off offset:576 nt
	s_mov_b32 s98, 0x20000
	s_mov_b32 s99, 0
	v_lshl_add_u64 v[214:215], v[216:217], 0, s[98:99]
	global_load_dwordx4 v[182:185], v[214:215], off nt
	global_load_dwordx4 v[186:189], v[214:215], off offset:64 nt
	global_load_dwordx4 v[190:193], v[214:215], off offset:512 nt
	global_load_dwordx4 v[194:197], v[214:215], off offset:576 nt
	s_mov_b32 s98, 0x40000
	s_mov_b32 s99, 0
	v_lshl_add_u64 v[214:215], v[216:217], 0, s[98:99]
	global_load_dwordx4 v[198:201], v[214:215], off nt
	global_load_dwordx4 v[202:205], v[214:215], off offset:64 nt
	global_load_dwordx4 v[206:209], v[214:215], off offset:512 nt
	global_load_dwordx4 v[210:213], v[214:215], off offset:576 nt
	v_readlane_b32 s49, v254, 33
	v_readlane_b32 s50, v254, 34
	v_readlane_b32 s51, v254, 35
	v_readlane_b32 s52, v254, 36
	v_readlane_b32 s53, v254, 37
	v_readlane_b32 s54, v254, 38
	v_readlane_b32 s55, v254, 39
	v_readlane_b32 s56, v254, 40
	v_readlane_b32 s57, v254, 41
	v_readlane_b32 s58, v254, 42
	v_readlane_b32 s59, v254, 43
	v_readlane_b32 s60, v254, 44
	v_readlane_b32 s61, v254, 45
	s_waitcnt vmcnt(11)
	v_pk_add_f32 v[128:129], v[128:129], v[168:169]
	v_pk_add_f32 v[126:127], v[126:127], v[166:167]
	v_cvt_pk_bf16_f32 v167, v128, v129
	v_cvt_pk_bf16_f32 v166, v126, v127
	global_store_dwordx4 v[160:161], v[126:129], off nt
	global_store_dwordx2 v[162:163], v[166:167], off
	s_waitcnt vmcnt(12)
	v_pk_add_f32 v[124:125], v[124:125], v[172:173]
	v_pk_add_f32 v[122:123], v[122:123], v[170:171]
	v_cvt_pk_bf16_f32 v171, v124, v125
	v_cvt_pk_bf16_f32 v170, v122, v123
	global_store_dwordx4 v[160:161], v[122:125], off offset:64 nt
	global_store_dwordx2 v[162:163], v[170:171], off offset:32
	s_waitcnt vmcnt(13)
	v_pk_add_f32 v[176:177], v[120:121], v[176:177]
	v_pk_add_f32 v[174:175], v[118:119], v[174:175]
	v_cvt_pk_bf16_f32 v119, v176, v177
	v_cvt_pk_bf16_f32 v118, v174, v175
	global_store_dwordx4 v[160:161], v[174:177], off offset:512 nt
	global_store_dwordx2 v[162:163], v[118:119], off offset:256
	v_mul_f32_e32 v120, v127, v127
	v_mul_f32_e32 v121, v129, v129
	v_fmac_f32_e32 v120, v126, v126
	v_fmac_f32_e32 v121, v128, v128
	v_add_f32_e32 v120, v120, v121
	v_mul_f32_e32 v121, v123, v123
	v_mul_f32_e32 v123, v125, v125
	v_fmac_f32_e32 v121, v122, v122
	v_fmac_f32_e32 v123, v124, v124
	v_add_f32_e32 v121, v121, v123
	v_add_f32_e32 v120, v120, v121
	v_mul_f32_e32 v121, v175, v175
	v_mul_f32_e32 v122, v177, v177
	v_fmac_f32_e32 v121, v174, v174
	v_fmac_f32_e32 v122, v176, v176
	v_add_f32_e32 v121, v121, v122
	v_and_b32_e32 v119, 64, v151
	v_add_f32_e32 v124, v120, v121
	v_xor_b32_e32 v118, 16, v151
	v_add_u32_e32 v119, 64, v119
	v_cmp_lt_i32_e32 vcc, v118, v119
	s_waitcnt vmcnt(14)
	v_pk_add_f32 v[122:123], v[116:117], v[180:181]
	v_pk_add_f32 v[120:121], v[114:115], v[178:179]
	v_mul_f32_e32 v115, v123, v123
	v_mul_f32_e32 v114, v121, v121
	v_fmac_f32_e32 v114, v120, v120
	v_fmac_f32_e32 v115, v122, v122
	v_cndmask_b32_e32 v118, v151, v118, vcc
	v_add_f32_e32 v114, v114, v115
	v_lshlrev_b32_e32 v118, 2, v118
	v_add_f32_e32 v114, v124, v114
	ds_bpermute_b32 v115, v118, v114
	v_cmp_lt_i32_e32 vcc, v165, v119
	global_store_dwordx4 v[160:161], v[120:123], off offset:576 nt
	s_waitcnt lgkmcnt(0)
	v_add_f32_e32 v114, v114, v115
	v_cndmask_b32_e32 v116, v151, v165, vcc
	v_lshlrev_b32_e32 v116, 2, v116
	ds_bpermute_b32 v115, v116, v114
	v_cmp_eq_u32_e32 vcc, 0, v164
	v_cvt_pk_bf16_f32 v120, v120, v121
	v_cvt_pk_bf16_f32 v121, v122, v123
	global_store_dwordx2 v[162:163], v[120:121], off offset:288
	s_and_saveexec_b64 s[18:19], vcc
	s_cbranch_execz .LBB0_2123
	s_waitcnt lgkmcnt(0)
	v_add_f32_e32 v117, v114, v115
	s_lshl_b32 s20, s28, 2
	v_lshlrev_b64 v[114:115], 7, v[144:145]
	s_ashr_i32 s21, s20, 31
	v_lshl_add_u64 v[114:115], s[10:11], 0, v[114:115]
	v_lshl_add_u64 v[114:115], s[20:21], 2, v[114:115]
	s_lshl_b32 s4, s35, 2
	v_lshl_add_u64 v[114:115], v[114:115], 0, s[4:5]
	global_store_dword v[114:115], v117, off
.LBB0_2123:
	s_or_b64 exec, exec, s[18:19]
	s_mov_b32 s98, 0x60000
	s_mov_b32 s99, 0
	v_lshl_add_u64 v[214:215], v[216:217], 0, s[98:99]
	global_load_dwordx4 v[166:169], v[214:215], off nt
	global_load_dwordx4 v[170:173], v[214:215], off offset:64 nt
	global_load_dwordx4 v[174:177], v[214:215], off offset:512 nt
	global_load_dwordx4 v[178:181], v[214:215], off offset:576 nt
	v_add_u32_e32 v114, 16, v144
	s_waitcnt lgkmcnt(0)
	v_ashrrev_i32_e32 v115, 31, v114
	v_lshlrev_b64 v[120:121], 11, v[114:115]
	v_readlane_b32 s48, v254, 32
	v_lshl_add_u64 v[124:125], v[120:121], 0, v[142:143]
	v_readlane_b32 s62, v254, 46
	v_readlane_b32 s63, v254, 47
	v_readlane_b32 s49, v254, 33
	v_readlane_b32 s50, v254, 34
	v_lshl_add_u64 v[126:127], v[124:125], 2, s[62:63]
	v_lshl_add_u64 v[124:125], v[124:125], 1, s[88:89]
	v_readlane_b32 s51, v254, 35
	v_readlane_b32 s52, v254, 36
	v_readlane_b32 s53, v254, 37
	v_readlane_b32 s54, v254, 38
	v_readlane_b32 s55, v254, 39
	v_readlane_b32 s56, v254, 40
	v_readlane_b32 s57, v254, 41
	v_readlane_b32 s58, v254, 42
	v_readlane_b32 s59, v254, 43
	v_readlane_b32 s60, v254, 44
	v_readlane_b32 s61, v254, 45
	s_waitcnt vmcnt(19)
	v_pk_add_f32 v[112:113], v[112:113], v[184:185]
	v_pk_add_f32 v[110:111], v[110:111], v[182:183]
	v_cvt_pk_bf16_f32 v183, v112, v113
	v_cvt_pk_bf16_f32 v182, v110, v111
	global_store_dwordx4 v[126:127], v[110:113], off nt
	global_store_dwordx2 v[124:125], v[182:183], off
	v_mul_f32_e32 v111, v111, v111
	v_mul_f32_e32 v113, v113, v113
	v_fmac_f32_e32 v111, v110, v110
	v_fmac_f32_e32 v113, v112, v112
	v_add_f32_e32 v110, v111, v113
	s_waitcnt vmcnt(20)
	v_pk_add_f32 v[108:109], v[108:109], v[188:189]
	v_pk_add_f32 v[106:107], v[106:107], v[186:187]
	v_cvt_pk_bf16_f32 v187, v108, v109
	v_cvt_pk_bf16_f32 v186, v106, v107
	global_store_dwordx4 v[126:127], v[106:109], off offset:64 nt
	global_store_dwordx2 v[124:125], v[186:187], off offset:32
	v_mul_f32_e32 v107, v107, v107
	v_mul_f32_e32 v109, v109, v109
	v_fmac_f32_e32 v107, v106, v106
	v_fmac_f32_e32 v109, v108, v108
	v_add_f32_e32 v106, v107, v109
	v_add_f32_e32 v106, v110, v106
	s_waitcnt vmcnt(21)
	v_pk_add_f32 v[104:105], v[104:105], v[192:193]
	v_pk_add_f32 v[102:103], v[102:103], v[190:191]
	v_cvt_pk_bf16_f32 v191, v104, v105
	v_cvt_pk_bf16_f32 v190, v102, v103
	global_store_dwordx4 v[126:127], v[102:105], off offset:512 nt
	global_store_dwordx2 v[124:125], v[190:191], off offset:256
	v_mul_f32_e32 v103, v103, v103
	v_mul_f32_e32 v105, v105, v105
	v_fmac_f32_e32 v103, v102, v102
	v_fmac_f32_e32 v105, v104, v104
	v_add_f32_e32 v102, v103, v105
	v_add_f32_e32 v104, v106, v102
	s_waitcnt vmcnt(22)
	v_pk_add_f32 v[102:103], v[100:101], v[196:197]
	v_pk_add_f32 v[100:101], v[98:99], v[194:195]
	v_mul_f32_e32 v99, v103, v103
	v_mul_f32_e32 v98, v101, v101
	v_fmac_f32_e32 v98, v100, v100
	v_fmac_f32_e32 v99, v102, v102
	v_add_f32_e32 v98, v98, v99
	v_add_f32_e32 v98, v104, v98
	ds_bpermute_b32 v99, v118, v98
	global_store_dwordx4 v[126:127], v[100:103], off offset:576 nt
	s_waitcnt lgkmcnt(0)
	v_add_f32_e32 v98, v98, v99
	ds_bpermute_b32 v99, v116, v98
	v_cvt_pk_bf16_f32 v100, v100, v101
	v_cvt_pk_bf16_f32 v101, v102, v103
	global_store_dwordx2 v[124:125], v[100:101], off offset:288
	s_and_saveexec_b64 s[18:19], vcc
	s_cbranch_execz .LBB0_2125
	s_waitcnt lgkmcnt(0)
	v_add_f32_e32 v100, v98, v99
	s_lshl_b32 s20, s28, 2
	v_lshlrev_b64 v[98:99], 7, v[114:115]
	s_ashr_i32 s21, s20, 31
	v_lshl_add_u64 v[98:99], s[10:11], 0, v[98:99]
	v_lshl_add_u64 v[98:99], s[20:21], 2, v[98:99]
	s_lshl_b32 s4, s35, 2
	v_lshl_add_u64 v[98:99], v[98:99], 0, s[4:5]
	global_store_dword v[98:99], v100, off
.LBB0_2125:
	s_or_b64 exec, exec, s[18:19]
	s_mov_b32 s98, 0x100000
	s_mov_b32 s99, 0
	v_lshl_add_u64 v[214:215], v[216:217], 0, s[98:99]
	global_load_dwordx4 v[182:185], v[214:215], off nt
	global_load_dwordx4 v[186:189], v[214:215], off offset:64 nt
	global_load_dwordx4 v[190:193], v[214:215], off offset:512 nt
	global_load_dwordx4 v[194:197], v[214:215], off offset:576 nt
	v_add_u32_e32 v98, 32, v144
	s_waitcnt lgkmcnt(0)
	v_ashrrev_i32_e32 v99, 31, v98
	v_lshlrev_b64 v[100:101], 11, v[98:99]
	v_readlane_b32 s48, v254, 32
	v_lshl_add_u64 v[104:105], v[100:101], 0, v[142:143]
	v_readlane_b32 s62, v254, 46
	v_readlane_b32 s63, v254, 47
	v_readlane_b32 s49, v254, 33
	v_readlane_b32 s50, v254, 34
	v_lshl_add_u64 v[106:107], v[104:105], 2, s[62:63]
	v_lshl_add_u64 v[104:105], v[104:105], 1, s[88:89]
	v_readlane_b32 s51, v254, 35
	v_readlane_b32 s52, v254, 36
	v_readlane_b32 s53, v254, 37
	v_readlane_b32 s54, v254, 38
	v_readlane_b32 s55, v254, 39
	v_readlane_b32 s56, v254, 40
	v_readlane_b32 s57, v254, 41
	v_readlane_b32 s58, v254, 42
	v_readlane_b32 s59, v254, 43
	v_readlane_b32 s60, v254, 44
	v_readlane_b32 s61, v254, 45
	s_waitcnt vmcnt(27)
	v_pk_add_f32 v[96:97], v[96:97], v[200:201]
	v_pk_add_f32 v[94:95], v[94:95], v[198:199]
	v_cvt_pk_bf16_f32 v199, v96, v97
	v_cvt_pk_bf16_f32 v198, v94, v95
	global_store_dwordx4 v[106:107], v[94:97], off nt
	global_store_dwordx2 v[104:105], v[198:199], off
	v_mul_f32_e32 v95, v95, v95
	v_mul_f32_e32 v97, v97, v97
	v_fmac_f32_e32 v95, v94, v94
	v_fmac_f32_e32 v97, v96, v96
	v_add_f32_e32 v94, v95, v97
	s_waitcnt vmcnt(28)
	v_pk_add_f32 v[92:93], v[92:93], v[204:205]
	v_pk_add_f32 v[90:91], v[90:91], v[202:203]
	v_cvt_pk_bf16_f32 v203, v92, v93
	v_cvt_pk_bf16_f32 v202, v90, v91
	global_store_dwordx4 v[106:107], v[90:93], off offset:64 nt
	global_store_dwordx2 v[104:105], v[202:203], off offset:32
	v_mul_f32_e32 v91, v91, v91
	v_mul_f32_e32 v93, v93, v93
	v_fmac_f32_e32 v91, v90, v90
	v_fmac_f32_e32 v93, v92, v92
	v_add_f32_e32 v90, v91, v93
	v_add_f32_e32 v90, v94, v90
	s_waitcnt vmcnt(29)
	v_pk_add_f32 v[88:89], v[88:89], v[208:209]
	v_pk_add_f32 v[86:87], v[86:87], v[206:207]
	v_cvt_pk_bf16_f32 v207, v88, v89
	v_cvt_pk_bf16_f32 v206, v86, v87
	global_store_dwordx4 v[106:107], v[86:89], off offset:512 nt
	global_store_dwordx2 v[104:105], v[206:207], off offset:256
	v_mul_f32_e32 v87, v87, v87
	v_mul_f32_e32 v89, v89, v89
	v_fmac_f32_e32 v87, v86, v86
	v_fmac_f32_e32 v89, v88, v88
	v_add_f32_e32 v86, v87, v89
	v_add_f32_e32 v88, v90, v86
	s_waitcnt vmcnt(30)
	v_pk_add_f32 v[86:87], v[84:85], v[212:213]
	v_pk_add_f32 v[84:85], v[82:83], v[210:211]
	v_mul_f32_e32 v83, v87, v87
	v_mul_f32_e32 v82, v85, v85
	v_fmac_f32_e32 v82, v84, v84
	v_fmac_f32_e32 v83, v86, v86
	v_add_f32_e32 v82, v82, v83
	v_add_f32_e32 v82, v88, v82
	ds_bpermute_b32 v83, v118, v82
	global_store_dwordx4 v[106:107], v[84:87], off offset:576 nt
	s_waitcnt lgkmcnt(0)
	v_add_f32_e32 v82, v82, v83
	ds_bpermute_b32 v83, v116, v82
	v_cvt_pk_bf16_f32 v84, v84, v85
	v_cvt_pk_bf16_f32 v85, v86, v87
	global_store_dwordx2 v[104:105], v[84:85], off offset:288
	s_and_saveexec_b64 s[18:19], vcc
	s_cbranch_execz .LBB0_2127
	s_waitcnt lgkmcnt(0)
	v_add_f32_e32 v84, v82, v83
	s_lshl_b32 s20, s28, 2
	v_lshlrev_b64 v[82:83], 7, v[98:99]
	s_ashr_i32 s21, s20, 31
	v_lshl_add_u64 v[82:83], s[10:11], 0, v[82:83]
	v_lshl_add_u64 v[82:83], s[20:21], 2, v[82:83]
	s_lshl_b32 s4, s35, 2
	v_lshl_add_u64 v[82:83], v[82:83], 0, s[4:5]
	global_store_dword v[82:83], v84, off
.LBB0_2127:
	s_or_b64 exec, exec, s[18:19]
	s_mov_b32 s98, 0x120000
	s_mov_b32 s99, 0
	v_lshl_add_u64 v[214:215], v[216:217], 0, s[98:99]
	global_load_dwordx4 v[198:201], v[214:215], off nt
	global_load_dwordx4 v[202:205], v[214:215], off offset:64 nt
	global_load_dwordx4 v[206:209], v[214:215], off offset:512 nt
	global_load_dwordx4 v[210:213], v[214:215], off offset:576 nt
	v_add_u32_e32 v82, 48, v144
	s_waitcnt lgkmcnt(0)
	v_ashrrev_i32_e32 v83, 31, v82
	v_lshlrev_b64 v[84:85], 11, v[82:83]
	v_readlane_b32 s48, v254, 32
	v_lshl_add_u64 v[88:89], v[84:85], 0, v[142:143]
	v_readlane_b32 s62, v254, 46
	v_readlane_b32 s63, v254, 47
	v_readlane_b32 s49, v254, 33
	v_readlane_b32 s50, v254, 34
	v_lshl_add_u64 v[90:91], v[88:89], 2, s[62:63]
	v_lshl_add_u64 v[88:89], v[88:89], 1, s[88:89]
	v_readlane_b32 s51, v254, 35
	v_readlane_b32 s52, v254, 36
	v_readlane_b32 s53, v254, 37
	v_readlane_b32 s54, v254, 38
	v_readlane_b32 s55, v254, 39
	v_readlane_b32 s56, v254, 40
	v_readlane_b32 s57, v254, 41
	v_readlane_b32 s58, v254, 42
	v_readlane_b32 s59, v254, 43
	v_readlane_b32 s60, v254, 44
	v_readlane_b32 s61, v254, 45
	s_waitcnt vmcnt(27)
	v_pk_add_f32 v[80:81], v[80:81], v[168:169]
	v_pk_add_f32 v[78:79], v[78:79], v[166:167]
	v_cvt_pk_bf16_f32 v167, v80, v81
	v_cvt_pk_bf16_f32 v166, v78, v79
	global_store_dwordx4 v[90:91], v[78:81], off nt
	global_store_dwordx2 v[88:89], v[166:167], off
	v_mul_f32_e32 v79, v79, v79
	v_mul_f32_e32 v81, v81, v81
	v_fmac_f32_e32 v79, v78, v78
	v_fmac_f32_e32 v81, v80, v80
	v_add_f32_e32 v78, v79, v81
	s_waitcnt vmcnt(28)
	v_pk_add_f32 v[76:77], v[76:77], v[172:173]
	v_pk_add_f32 v[74:75], v[74:75], v[170:171]
	v_cvt_pk_bf16_f32 v171, v76, v77
	v_cvt_pk_bf16_f32 v170, v74, v75
	global_store_dwordx4 v[90:91], v[74:77], off offset:64 nt
	global_store_dwordx2 v[88:89], v[170:171], off offset:32
	v_mul_f32_e32 v75, v75, v75
	v_mul_f32_e32 v77, v77, v77
	v_fmac_f32_e32 v75, v74, v74
	v_fmac_f32_e32 v77, v76, v76
	v_add_f32_e32 v74, v75, v77
	v_add_f32_e32 v74, v78, v74
	s_waitcnt vmcnt(29)
	v_pk_add_f32 v[72:73], v[72:73], v[176:177]
	v_pk_add_f32 v[70:71], v[70:71], v[174:175]
	v_cvt_pk_bf16_f32 v175, v72, v73
	v_cvt_pk_bf16_f32 v174, v70, v71
	global_store_dwordx4 v[90:91], v[70:73], off offset:512 nt
	global_store_dwordx2 v[88:89], v[174:175], off offset:256
	v_mul_f32_e32 v71, v71, v71
	v_mul_f32_e32 v73, v73, v73
	v_fmac_f32_e32 v71, v70, v70
	v_fmac_f32_e32 v73, v72, v72
	v_add_f32_e32 v70, v71, v73
	v_add_f32_e32 v72, v74, v70
	s_waitcnt vmcnt(30)
	v_pk_add_f32 v[70:71], v[68:69], v[180:181]
	v_pk_add_f32 v[68:69], v[66:67], v[178:179]
	v_mul_f32_e32 v67, v71, v71
	v_mul_f32_e32 v66, v69, v69
	v_fmac_f32_e32 v66, v68, v68
	v_fmac_f32_e32 v67, v70, v70
	v_add_f32_e32 v66, v66, v67
	v_add_f32_e32 v66, v72, v66
	ds_bpermute_b32 v67, v118, v66
	global_store_dwordx4 v[90:91], v[68:71], off offset:576 nt
	s_waitcnt lgkmcnt(0)
	v_add_f32_e32 v66, v66, v67
	ds_bpermute_b32 v67, v116, v66
	v_cvt_pk_bf16_f32 v68, v68, v69
	v_cvt_pk_bf16_f32 v69, v70, v71
	global_store_dwordx2 v[88:89], v[68:69], off offset:288
	s_and_saveexec_b64 s[18:19], vcc
	s_cbranch_execz .LBB0_2129
	s_waitcnt lgkmcnt(0)
	v_add_f32_e32 v68, v66, v67
	s_lshl_b32 s20, s28, 2
	v_lshlrev_b64 v[66:67], 7, v[82:83]
	s_ashr_i32 s21, s20, 31
	v_lshl_add_u64 v[66:67], s[10:11], 0, v[66:67]
	v_lshl_add_u64 v[66:67], s[20:21], 2, v[66:67]
	s_lshl_b32 s4, s35, 2
	v_lshl_add_u64 v[66:67], v[66:67], 0, s[4:5]
	global_store_dword v[66:67], v68, off
.LBB0_2129:
	s_or_b64 exec, exec, s[18:19]
	s_mov_b32 s98, 0x140000
	s_mov_b32 s99, 0
	v_lshl_add_u64 v[214:215], v[216:217], 0, s[98:99]
	global_load_dwordx4 v[166:169], v[214:215], off nt
	global_load_dwordx4 v[170:173], v[214:215], off offset:64 nt
	global_load_dwordx4 v[174:177], v[214:215], off offset:512 nt
	global_load_dwordx4 v[178:181], v[214:215], off offset:576 nt
	v_add_u32_e32 v66, 0x80, v144
	s_waitcnt lgkmcnt(0)
	v_ashrrev_i32_e32 v67, 31, v66
	v_lshlrev_b64 v[68:69], 11, v[66:67]
	v_readlane_b32 s48, v254, 32
	v_lshl_add_u64 v[72:73], v[68:69], 0, v[142:143]
	v_readlane_b32 s62, v254, 46
	v_readlane_b32 s63, v254, 47
	v_readlane_b32 s49, v254, 33
	v_readlane_b32 s50, v254, 34
	v_lshl_add_u64 v[74:75], v[72:73], 2, s[62:63]
	v_lshl_add_u64 v[72:73], v[72:73], 1, s[88:89]
	v_readlane_b32 s51, v254, 35
	v_readlane_b32 s52, v254, 36
	v_readlane_b32 s53, v254, 37
	v_readlane_b32 s54, v254, 38
	v_readlane_b32 s55, v254, 39
	v_readlane_b32 s56, v254, 40
	v_readlane_b32 s57, v254, 41
	v_readlane_b32 s58, v254, 42
	v_readlane_b32 s59, v254, 43
	v_readlane_b32 s60, v254, 44
	v_readlane_b32 s61, v254, 45
	s_waitcnt vmcnt(27)
	v_pk_add_f32 v[64:65], v[64:65], v[184:185]
	v_pk_add_f32 v[62:63], v[62:63], v[182:183]
	v_cvt_pk_bf16_f32 v183, v64, v65
	v_cvt_pk_bf16_f32 v182, v62, v63
	global_store_dwordx4 v[74:75], v[62:65], off nt
	global_store_dwordx2 v[72:73], v[182:183], off
	v_mul_f32_e32 v63, v63, v63
	v_mul_f32_e32 v65, v65, v65
	v_fmac_f32_e32 v63, v62, v62
	v_fmac_f32_e32 v65, v64, v64
	v_add_f32_e32 v62, v63, v65
	s_waitcnt vmcnt(28)
	v_pk_add_f32 v[60:61], v[60:61], v[188:189]
	v_pk_add_f32 v[58:59], v[58:59], v[186:187]
	v_cvt_pk_bf16_f32 v187, v60, v61
	v_cvt_pk_bf16_f32 v186, v58, v59
	global_store_dwordx4 v[74:75], v[58:61], off offset:64 nt
	global_store_dwordx2 v[72:73], v[186:187], off offset:32
	v_mul_f32_e32 v59, v59, v59
	v_mul_f32_e32 v61, v61, v61
	v_fmac_f32_e32 v59, v58, v58
	v_fmac_f32_e32 v61, v60, v60
	v_add_f32_e32 v58, v59, v61
	v_add_f32_e32 v58, v62, v58
	s_waitcnt vmcnt(29)
	v_pk_add_f32 v[56:57], v[56:57], v[192:193]
	v_pk_add_f32 v[54:55], v[54:55], v[190:191]
	v_cvt_pk_bf16_f32 v191, v56, v57
	v_cvt_pk_bf16_f32 v190, v54, v55
	global_store_dwordx4 v[74:75], v[54:57], off offset:512 nt
	global_store_dwordx2 v[72:73], v[190:191], off offset:256
	v_mul_f32_e32 v55, v55, v55
	v_mul_f32_e32 v57, v57, v57
	v_fmac_f32_e32 v55, v54, v54
	v_fmac_f32_e32 v57, v56, v56
	v_add_f32_e32 v54, v55, v57
	v_add_f32_e32 v56, v58, v54
	s_waitcnt vmcnt(30)
	v_pk_add_f32 v[54:55], v[52:53], v[196:197]
	v_pk_add_f32 v[52:53], v[50:51], v[194:195]
	v_mul_f32_e32 v51, v55, v55
	v_mul_f32_e32 v50, v53, v53
	v_fmac_f32_e32 v50, v52, v52
	v_fmac_f32_e32 v51, v54, v54
	v_add_f32_e32 v50, v50, v51
	v_add_f32_e32 v50, v56, v50
	ds_bpermute_b32 v51, v118, v50
	global_store_dwordx4 v[74:75], v[52:55], off offset:576 nt
	s_waitcnt lgkmcnt(0)
	v_add_f32_e32 v50, v50, v51
	ds_bpermute_b32 v51, v116, v50
	v_cvt_pk_bf16_f32 v52, v52, v53
	v_cvt_pk_bf16_f32 v53, v54, v55
	global_store_dwordx2 v[72:73], v[52:53], off offset:288
	s_and_saveexec_b64 s[18:19], vcc
	s_cbranch_execz .LBB0_2131
	s_waitcnt lgkmcnt(0)
	v_add_f32_e32 v52, v50, v51
	s_lshl_b32 s20, s28, 2
	v_lshlrev_b64 v[50:51], 7, v[66:67]
	s_ashr_i32 s21, s20, 31
	v_lshl_add_u64 v[50:51], s[10:11], 0, v[50:51]
	v_lshl_add_u64 v[50:51], s[20:21], 2, v[50:51]
	s_lshl_b32 s4, s35, 2
	v_lshl_add_u64 v[50:51], v[50:51], 0, s[4:5]
	global_store_dword v[50:51], v52, off
.LBB0_2131:
	s_or_b64 exec, exec, s[18:19]
	s_mov_b32 s98, 0x160000
	s_mov_b32 s99, 0
	v_lshl_add_u64 v[214:215], v[216:217], 0, s[98:99]
	global_load_dwordx4 v[182:185], v[214:215], off nt
	global_load_dwordx4 v[186:189], v[214:215], off offset:64 nt
	global_load_dwordx4 v[190:193], v[214:215], off offset:512 nt
	global_load_dwordx4 v[194:197], v[214:215], off offset:576 nt
	v_add_u32_e32 v50, 0x90, v144
	s_waitcnt lgkmcnt(0)
	v_ashrrev_i32_e32 v51, 31, v50
	v_lshlrev_b64 v[52:53], 11, v[50:51]
	v_readlane_b32 s48, v254, 32
	v_lshl_add_u64 v[56:57], v[52:53], 0, v[142:143]
	v_readlane_b32 s62, v254, 46
	v_readlane_b32 s63, v254, 47
	v_readlane_b32 s49, v254, 33
	v_readlane_b32 s50, v254, 34
	v_lshl_add_u64 v[58:59], v[56:57], 2, s[62:63]
	v_lshl_add_u64 v[56:57], v[56:57], 1, s[88:89]
	v_readlane_b32 s51, v254, 35
	v_readlane_b32 s52, v254, 36
	v_readlane_b32 s53, v254, 37
	v_readlane_b32 s54, v254, 38
	v_readlane_b32 s55, v254, 39
	v_readlane_b32 s56, v254, 40
	v_readlane_b32 s57, v254, 41
	v_readlane_b32 s58, v254, 42
	v_readlane_b32 s59, v254, 43
	v_readlane_b32 s60, v254, 44
	v_readlane_b32 s61, v254, 45
	s_waitcnt vmcnt(27)
	v_pk_add_f32 v[48:49], v[48:49], v[200:201]
	v_pk_add_f32 v[46:47], v[46:47], v[198:199]
	v_cvt_pk_bf16_f32 v199, v48, v49
	v_cvt_pk_bf16_f32 v198, v46, v47
	global_store_dwordx4 v[58:59], v[46:49], off nt
	global_store_dwordx2 v[56:57], v[198:199], off
	v_mul_f32_e32 v47, v47, v47
	v_mul_f32_e32 v49, v49, v49
	v_fmac_f32_e32 v47, v46, v46
	v_fmac_f32_e32 v49, v48, v48
	v_add_f32_e32 v46, v47, v49
	s_waitcnt vmcnt(28)
	v_pk_add_f32 v[44:45], v[44:45], v[204:205]
	v_pk_add_f32 v[42:43], v[42:43], v[202:203]
	v_cvt_pk_bf16_f32 v203, v44, v45
	v_cvt_pk_bf16_f32 v202, v42, v43
	global_store_dwordx4 v[58:59], v[42:45], off offset:64 nt
	global_store_dwordx2 v[56:57], v[202:203], off offset:32
	v_mul_f32_e32 v43, v43, v43
	v_mul_f32_e32 v45, v45, v45
	v_fmac_f32_e32 v43, v42, v42
	v_fmac_f32_e32 v45, v44, v44
	v_add_f32_e32 v42, v43, v45
	v_add_f32_e32 v42, v46, v42
	s_waitcnt vmcnt(29)
	v_pk_add_f32 v[40:41], v[40:41], v[208:209]
	v_pk_add_f32 v[38:39], v[38:39], v[206:207]
	v_cvt_pk_bf16_f32 v207, v40, v41
	v_cvt_pk_bf16_f32 v206, v38, v39
	global_store_dwordx4 v[58:59], v[38:41], off offset:512 nt
	global_store_dwordx2 v[56:57], v[206:207], off offset:256
	v_mul_f32_e32 v39, v39, v39
	v_mul_f32_e32 v41, v41, v41
	v_fmac_f32_e32 v39, v38, v38
	v_fmac_f32_e32 v41, v40, v40
	v_add_f32_e32 v38, v39, v41
	v_add_f32_e32 v40, v42, v38
	s_waitcnt vmcnt(30)
	v_pk_add_f32 v[38:39], v[36:37], v[212:213]
	v_pk_add_f32 v[36:37], v[34:35], v[210:211]
	v_mul_f32_e32 v35, v39, v39
	v_mul_f32_e32 v34, v37, v37
	v_fmac_f32_e32 v34, v36, v36
	v_fmac_f32_e32 v35, v38, v38
	v_add_f32_e32 v34, v34, v35
	v_add_f32_e32 v34, v40, v34
	ds_bpermute_b32 v35, v118, v34
	global_store_dwordx4 v[58:59], v[36:39], off offset:576 nt
	s_waitcnt lgkmcnt(0)
	v_add_f32_e32 v34, v34, v35
	ds_bpermute_b32 v35, v116, v34
	v_cvt_pk_bf16_f32 v36, v36, v37
	v_cvt_pk_bf16_f32 v37, v38, v39
	global_store_dwordx2 v[56:57], v[36:37], off offset:288
	s_and_saveexec_b64 s[18:19], vcc
	s_cbranch_execz .LBB0_2133
	s_waitcnt lgkmcnt(0)
	v_add_f32_e32 v36, v34, v35
	s_lshl_b32 s20, s28, 2
	v_lshlrev_b64 v[34:35], 7, v[50:51]
	s_ashr_i32 s21, s20, 31
	v_lshl_add_u64 v[34:35], s[10:11], 0, v[34:35]
	v_lshl_add_u64 v[34:35], s[20:21], 2, v[34:35]
	s_lshl_b32 s4, s35, 2
	v_lshl_add_u64 v[34:35], v[34:35], 0, s[4:5]
	global_store_dword v[34:35], v36, off
.LBB0_2133:
	s_or_b64 exec, exec, s[18:19]
	v_add_u32_e32 v34, 0xa0, v144
	s_waitcnt lgkmcnt(0)
	v_ashrrev_i32_e32 v35, 31, v34
	v_lshlrev_b64 v[36:37], 11, v[34:35]
	v_readlane_b32 s48, v254, 32
	v_lshl_add_u64 v[40:41], v[36:37], 0, v[142:143]
	v_readlane_b32 s62, v254, 46
	v_readlane_b32 s63, v254, 47
	v_readlane_b32 s49, v254, 33
	v_readlane_b32 s50, v254, 34
	v_lshl_add_u64 v[42:43], v[40:41], 2, s[62:63]
	v_lshl_add_u64 v[40:41], v[40:41], 1, s[88:89]
	v_readlane_b32 s51, v254, 35
	v_readlane_b32 s52, v254, 36
	v_readlane_b32 s53, v254, 37
	v_readlane_b32 s54, v254, 38
	v_readlane_b32 s55, v254, 39
	v_readlane_b32 s56, v254, 40
	v_readlane_b32 s57, v254, 41
	v_readlane_b32 s58, v254, 42
	v_readlane_b32 s59, v254, 43
	v_readlane_b32 s60, v254, 44
	v_readlane_b32 s61, v254, 45
	s_waitcnt vmcnt(23)
	v_pk_add_f32 v[32:33], v[32:33], v[168:169]
	v_pk_add_f32 v[30:31], v[30:31], v[166:167]
	v_cvt_pk_bf16_f32 v167, v32, v33
	v_cvt_pk_bf16_f32 v166, v30, v31
	global_store_dwordx4 v[42:43], v[30:33], off nt
	global_store_dwordx2 v[40:41], v[166:167], off
	v_mul_f32_e32 v31, v31, v31
	v_mul_f32_e32 v33, v33, v33
	v_fmac_f32_e32 v31, v30, v30
	v_fmac_f32_e32 v33, v32, v32
	v_add_f32_e32 v30, v31, v33
	s_waitcnt vmcnt(24)
	v_pk_add_f32 v[28:29], v[28:29], v[172:173]
	v_pk_add_f32 v[26:27], v[26:27], v[170:171]
	v_cvt_pk_bf16_f32 v171, v28, v29
	v_cvt_pk_bf16_f32 v170, v26, v27
	global_store_dwordx4 v[42:43], v[26:29], off offset:64 nt
	global_store_dwordx2 v[40:41], v[170:171], off offset:32
	v_mul_f32_e32 v27, v27, v27
	v_mul_f32_e32 v29, v29, v29
	v_fmac_f32_e32 v27, v26, v26
	v_fmac_f32_e32 v29, v28, v28
	v_add_f32_e32 v26, v27, v29
	v_add_f32_e32 v26, v30, v26
	s_waitcnt vmcnt(25)
	v_pk_add_f32 v[24:25], v[24:25], v[176:177]
	v_pk_add_f32 v[22:23], v[22:23], v[174:175]
	v_cvt_pk_bf16_f32 v175, v24, v25
	v_cvt_pk_bf16_f32 v174, v22, v23
	global_store_dwordx4 v[42:43], v[22:25], off offset:512 nt
	global_store_dwordx2 v[40:41], v[174:175], off offset:256
	v_mul_f32_e32 v23, v23, v23
	v_mul_f32_e32 v25, v25, v25
	v_fmac_f32_e32 v23, v22, v22
	v_fmac_f32_e32 v25, v24, v24
	v_add_f32_e32 v22, v23, v25
	v_add_f32_e32 v24, v26, v22
	s_waitcnt vmcnt(26)
	v_pk_add_f32 v[22:23], v[20:21], v[180:181]
	v_pk_add_f32 v[20:21], v[18:19], v[178:179]
	v_mul_f32_e32 v19, v23, v23
	v_mul_f32_e32 v18, v21, v21
	v_fmac_f32_e32 v18, v20, v20
	v_fmac_f32_e32 v19, v22, v22
	v_add_f32_e32 v18, v18, v19
	v_add_f32_e32 v18, v24, v18
	ds_bpermute_b32 v19, v118, v18
	global_store_dwordx4 v[42:43], v[20:23], off offset:576 nt
	s_waitcnt lgkmcnt(0)
	v_add_f32_e32 v18, v18, v19
	ds_bpermute_b32 v19, v116, v18
	v_cvt_pk_bf16_f32 v20, v20, v21
	v_cvt_pk_bf16_f32 v21, v22, v23
	global_store_dwordx2 v[40:41], v[20:21], off offset:288
	s_and_saveexec_b64 s[18:19], vcc
	s_cbranch_execz .LBB0_2135
	s_waitcnt lgkmcnt(0)
	v_add_f32_e32 v20, v18, v19
	s_lshl_b32 s20, s28, 2
	v_lshlrev_b64 v[18:19], 7, v[34:35]
	s_ashr_i32 s21, s20, 31
	v_lshl_add_u64 v[18:19], s[10:11], 0, v[18:19]
	v_lshl_add_u64 v[18:19], s[20:21], 2, v[18:19]
	s_lshl_b32 s4, s35, 2
	v_lshl_add_u64 v[18:19], v[18:19], 0, s[4:5]
	global_store_dword v[18:19], v20, off
.LBB0_2135:
	s_or_b64 exec, exec, s[18:19]
	v_add_u32_e32 v18, 0xb0, v144
	s_waitcnt lgkmcnt(0)
	v_ashrrev_i32_e32 v19, 31, v18
	v_lshlrev_b64 v[20:21], 11, v[18:19]
	v_readlane_b32 s48, v254, 32
	v_lshl_add_u64 v[24:25], v[20:21], 0, v[142:143]
	v_readlane_b32 s62, v254, 46
	v_readlane_b32 s63, v254, 47
	v_readlane_b32 s49, v254, 33
	v_readlane_b32 s50, v254, 34
	v_lshl_add_u64 v[26:27], v[24:25], 2, s[62:63]
	v_lshl_add_u64 v[24:25], v[24:25], 1, s[88:89]
	v_readlane_b32 s51, v254, 35
	v_readlane_b32 s52, v254, 36
	v_readlane_b32 s53, v254, 37
	v_readlane_b32 s54, v254, 38
	v_readlane_b32 s55, v254, 39
	v_readlane_b32 s56, v254, 40
	v_readlane_b32 s57, v254, 41
	v_readlane_b32 s58, v254, 42
	v_readlane_b32 s59, v254, 43
	v_readlane_b32 s60, v254, 44
	v_readlane_b32 s61, v254, 45
	s_waitcnt vmcnt(19)
	v_pk_add_f32 v[16:17], v[16:17], v[184:185]
	v_pk_add_f32 v[14:15], v[14:15], v[182:183]
	v_cvt_pk_bf16_f32 v183, v16, v17
	v_cvt_pk_bf16_f32 v182, v14, v15
	global_store_dwordx4 v[26:27], v[14:17], off nt
	global_store_dwordx2 v[24:25], v[182:183], off
	v_mul_f32_e32 v15, v15, v15
	v_mul_f32_e32 v17, v17, v17
	v_fmac_f32_e32 v15, v14, v14
	v_fmac_f32_e32 v17, v16, v16
	v_add_f32_e32 v14, v15, v17
	s_waitcnt vmcnt(20)
	v_pk_add_f32 v[12:13], v[12:13], v[188:189]
	v_pk_add_f32 v[10:11], v[10:11], v[186:187]
	v_cvt_pk_bf16_f32 v187, v12, v13
	v_cvt_pk_bf16_f32 v186, v10, v11
	global_store_dwordx4 v[26:27], v[10:13], off offset:64 nt
	global_store_dwordx2 v[24:25], v[186:187], off offset:32
	v_mul_f32_e32 v11, v11, v11
	v_mul_f32_e32 v13, v13, v13
	v_fmac_f32_e32 v11, v10, v10
	v_fmac_f32_e32 v13, v12, v12
	v_add_f32_e32 v10, v11, v13
	v_add_f32_e32 v10, v14, v10
	s_waitcnt vmcnt(21)
	v_pk_add_f32 v[8:9], v[8:9], v[192:193]
	v_pk_add_f32 v[6:7], v[6:7], v[190:191]
	v_cvt_pk_bf16_f32 v191, v8, v9
	v_cvt_pk_bf16_f32 v190, v6, v7
	global_store_dwordx4 v[26:27], v[6:9], off offset:512 nt
	global_store_dwordx2 v[24:25], v[190:191], off offset:256
	v_mul_f32_e32 v7, v7, v7
	v_mul_f32_e32 v9, v9, v9
	v_fmac_f32_e32 v7, v6, v6
	v_fmac_f32_e32 v9, v8, v8
	v_add_f32_e32 v6, v7, v9
	v_add_f32_e32 v8, v10, v6
	s_waitcnt vmcnt(22)
	v_pk_add_f32 v[6:7], v[4:5], v[196:197]
	v_pk_add_f32 v[4:5], v[2:3], v[194:195]
	v_mul_f32_e32 v3, v7, v7
	v_mul_f32_e32 v2, v5, v5
	v_fmac_f32_e32 v2, v4, v4
	v_fmac_f32_e32 v3, v6, v6
	v_add_f32_e32 v2, v2, v3
	v_add_f32_e32 v2, v8, v2
	ds_bpermute_b32 v3, v118, v2
	global_store_dwordx4 v[26:27], v[4:7], off offset:576 nt
	s_waitcnt lgkmcnt(0)
	v_add_f32_e32 v2, v2, v3
	ds_bpermute_b32 v3, v116, v2
	v_cvt_pk_bf16_f32 v4, v4, v5
	v_cvt_pk_bf16_f32 v5, v6, v7
	global_store_dwordx2 v[24:25], v[4:5], off offset:288
	s_and_saveexec_b64 s[18:19], vcc
	s_cbranch_execz .LBB0_2137
	s_waitcnt lgkmcnt(0)
	v_add_f32_e32 v4, v2, v3
	s_lshl_b32 s20, s28, 2
	v_lshlrev_b64 v[2:3], 7, v[18:19]
	s_ashr_i32 s21, s20, 31
	v_lshl_add_u64 v[2:3], s[10:11], 0, v[2:3]
	v_lshl_add_u64 v[2:3], s[20:21], 2, v[2:3]
	s_lshl_b32 s4, s35, 2
	v_lshl_add_u64 v[2:3], v[2:3], 0, s[4:5]
	global_store_dword v[2:3], v4, off

.LBB0_3117:
	s_lshl_b32 s6, s6, 8
	v_mov_b32_e32 v164, v1
	v_mov_b32_e32 v143, v146
	s_lshl_b32 s17, s4, 8
	s_add_i32 s6, s6, s42
	s_or_b32 s17, s17, s43
	v_add_u32_e32 v144, s6, v143
	v_lshl_add_u32 v142, v164, 2, s17
	v_ashrrev_i32_e32 v145, 31, v144
	v_ashrrev_i32_e32 v143, 31, v142
	v_lshlrev_b64 v[152:153], 11, v[144:145]
	v_readlane_b32 s52, v254, 32
	v_lshl_add_u64 v[156:157], v[152:153], 0, v[142:143]
	v_readlane_b32 s66, v254, 46
	v_readlane_b32 s67, v254, 47
	v_lshl_add_u64 v[162:163], v[156:157], 1, s[88:89]
	v_xor_b32_e32 v165, 32, v151
	v_lshl_add_u64 v[160:161], v[156:157], 2, s[66:67]
	v_mov_b32_e32 v216, v160
	v_mov_b32_e32 v217, v161
	global_load_dwordx4 v[166:169], v[216:217], off nt
	global_load_dwordx4 v[170:173], v[216:217], off offset:64 nt
	global_load_dwordx4 v[174:177], v[216:217], off offset:512 nt
	global_load_dwordx4 v[178:181], v[216:217], off offset:576 nt
	s_mov_b32 s98, 0x20000
	s_mov_b32 s99, 0
	v_lshl_add_u64 v[214:215], v[216:217], 0, s[98:99]
	global_load_dwordx4 v[182:185], v[214:215], off nt
	global_load_dwordx4 v[186:189], v[214:215], off offset:64 nt
	global_load_dwordx4 v[190:193], v[214:215], off offset:512 nt
	global_load_dwordx4 v[194:197], v[214:215], off offset:576 nt
	s_mov_b32 s98, 0x40000
	s_mov_b32 s99, 0
	v_lshl_add_u64 v[214:215], v[216:217], 0, s[98:99]
	global_load_dwordx4 v[198:201], v[214:215], off nt
	global_load_dwordx4 v[202:205], v[214:215], off offset:64 nt
	global_load_dwordx4 v[206:209], v[214:215], off offset:512 nt
	global_load_dwordx4 v[210:213], v[214:215], off offset:576 nt
	v_readlane_b32 s53, v254, 33
	v_readlane_b32 s54, v254, 34
	v_readlane_b32 s55, v254, 35
	v_readlane_b32 s56, v254, 36
	v_readlane_b32 s57, v254, 37
	v_readlane_b32 s58, v254, 38
	v_readlane_b32 s59, v254, 39
	v_readlane_b32 s60, v254, 40
	v_readlane_b32 s61, v254, 41
	v_readlane_b32 s62, v254, 42
	v_readlane_b32 s63, v254, 43
	v_readlane_b32 s64, v254, 44
	v_readlane_b32 s65, v254, 45
	s_waitcnt vmcnt(11)
	v_pk_add_f32 v[128:129], v[128:129], v[168:169]
	v_pk_add_f32 v[126:127], v[126:127], v[166:167]
	v_cvt_pk_bf16_f32 v167, v128, v129
	v_cvt_pk_bf16_f32 v166, v126, v127
	global_store_dwordx4 v[160:161], v[126:129], off nt
	global_store_dwordx2 v[162:163], v[166:167], off
	s_waitcnt vmcnt(12)
	v_pk_add_f32 v[124:125], v[124:125], v[172:173]
	v_pk_add_f32 v[122:123], v[122:123], v[170:171]
	v_cvt_pk_bf16_f32 v171, v124, v125
	v_cvt_pk_bf16_f32 v170, v122, v123
	global_store_dwordx4 v[160:161], v[122:125], off offset:64 nt
	global_store_dwordx2 v[162:163], v[170:171], off offset:32
	s_waitcnt vmcnt(13)
	v_pk_add_f32 v[176:177], v[120:121], v[176:177]
	v_pk_add_f32 v[174:175], v[118:119], v[174:175]
	v_cvt_pk_bf16_f32 v119, v176, v177
	v_cvt_pk_bf16_f32 v118, v174, v175
	global_store_dwordx4 v[160:161], v[174:177], off offset:512 nt
	global_store_dwordx2 v[162:163], v[118:119], off offset:256
	v_mul_f32_e32 v120, v127, v127
	v_mul_f32_e32 v121, v129, v129
	v_fmac_f32_e32 v120, v126, v126
	v_fmac_f32_e32 v121, v128, v128
	v_add_f32_e32 v120, v120, v121
	v_mul_f32_e32 v121, v123, v123
	v_mul_f32_e32 v123, v125, v125
	v_fmac_f32_e32 v121, v122, v122
	v_fmac_f32_e32 v123, v124, v124
	v_add_f32_e32 v121, v121, v123
	v_add_f32_e32 v120, v120, v121
	v_mul_f32_e32 v121, v175, v175
	v_mul_f32_e32 v122, v177, v177
	v_fmac_f32_e32 v121, v174, v174
	v_fmac_f32_e32 v122, v176, v176
	v_add_f32_e32 v121, v121, v122
	v_and_b32_e32 v119, 64, v151
	v_add_f32_e32 v124, v120, v121
	v_xor_b32_e32 v118, 16, v151
	v_add_u32_e32 v119, 64, v119
	v_cmp_lt_i32_e32 vcc, v118, v119
	s_waitcnt vmcnt(14)
	v_pk_add_f32 v[122:123], v[116:117], v[180:181]
	v_pk_add_f32 v[120:121], v[114:115], v[178:179]
	v_mul_f32_e32 v115, v123, v123
	v_mul_f32_e32 v114, v121, v121
	v_fmac_f32_e32 v114, v120, v120
	v_fmac_f32_e32 v115, v122, v122
	v_cndmask_b32_e32 v118, v151, v118, vcc
	v_add_f32_e32 v114, v114, v115
	v_lshlrev_b32_e32 v118, 2, v118
	v_add_f32_e32 v114, v124, v114
	ds_bpermute_b32 v115, v118, v114
	v_cmp_lt_i32_e32 vcc, v165, v119
	global_store_dwordx4 v[160:161], v[120:123], off offset:576 nt
	s_waitcnt lgkmcnt(0)
	v_add_f32_e32 v114, v114, v115
	v_cndmask_b32_e32 v116, v151, v165, vcc
	v_lshlrev_b32_e32 v116, 2, v116
	ds_bpermute_b32 v115, v116, v114
	v_cmp_eq_u32_e32 vcc, 0, v164
	v_cvt_pk_bf16_f32 v120, v120, v121
	v_cvt_pk_bf16_f32 v121, v122, v123
	global_store_dwordx2 v[162:163], v[120:121], off offset:288
	s_and_saveexec_b64 s[24:25], vcc
	s_cbranch_execz .LBB0_3119
	s_waitcnt lgkmcnt(0)
	v_add_f32_e32 v117, v114, v115
	s_lshl_b32 s26, s4, 2
	v_lshlrev_b64 v[114:115], 7, v[144:145]
	s_ashr_i32 s27, s26, 31
	v_lshl_add_u64 v[114:115], s[10:11], 0, v[114:115]
	v_lshl_add_u64 v[114:115], s[26:27], 2, v[114:115]
	s_lshl_b32 s6, s41, 2
	v_lshl_add_u64 v[114:115], v[114:115], 0, s[6:7]
	global_store_dword v[114:115], v117, off
.LBB0_3119:
	s_or_b64 exec, exec, s[24:25]
	s_mov_b32 s98, 0x60000
	s_mov_b32 s99, 0
	v_lshl_add_u64 v[214:215], v[216:217], 0, s[98:99]
	global_load_dwordx4 v[166:169], v[214:215], off nt
	global_load_dwordx4 v[170:173], v[214:215], off offset:64 nt
	global_load_dwordx4 v[174:177], v[214:215], off offset:512 nt
	global_load_dwordx4 v[178:181], v[214:215], off offset:576 nt
	v_add_u32_e32 v114, 16, v144
	s_waitcnt lgkmcnt(0)
	v_ashrrev_i32_e32 v115, 31, v114
	v_lshlrev_b64 v[120:121], 11, v[114:115]
	v_readlane_b32 s52, v254, 32
	v_lshl_add_u64 v[124:125], v[120:121], 0, v[142:143]
	v_readlane_b32 s66, v254, 46
	v_readlane_b32 s67, v254, 47
	v_readlane_b32 s53, v254, 33
	v_readlane_b32 s54, v254, 34
	v_lshl_add_u64 v[126:127], v[124:125], 2, s[66:67]
	v_lshl_add_u64 v[124:125], v[124:125], 1, s[88:89]
	v_readlane_b32 s55, v254, 35
	v_readlane_b32 s56, v254, 36
	v_readlane_b32 s57, v254, 37
	v_readlane_b32 s58, v254, 38
	v_readlane_b32 s59, v254, 39
	v_readlane_b32 s60, v254, 40
	v_readlane_b32 s61, v254, 41
	v_readlane_b32 s62, v254, 42
	v_readlane_b32 s63, v254, 43
	v_readlane_b32 s64, v254, 44
	v_readlane_b32 s65, v254, 45
	s_waitcnt vmcnt(19)
	v_pk_add_f32 v[112:113], v[112:113], v[184:185]
	v_pk_add_f32 v[110:111], v[110:111], v[182:183]
	v_cvt_pk_bf16_f32 v183, v112, v113
	v_cvt_pk_bf16_f32 v182, v110, v111
	global_store_dwordx4 v[126:127], v[110:113], off nt
	global_store_dwordx2 v[124:125], v[182:183], off
	v_mul_f32_e32 v111, v111, v111
	v_mul_f32_e32 v113, v113, v113
	v_fmac_f32_e32 v111, v110, v110
	v_fmac_f32_e32 v113, v112, v112
	v_add_f32_e32 v110, v111, v113
	s_waitcnt vmcnt(20)
	v_pk_add_f32 v[108:109], v[108:109], v[188:189]
	v_pk_add_f32 v[106:107], v[106:107], v[186:187]
	v_cvt_pk_bf16_f32 v187, v108, v109
	v_cvt_pk_bf16_f32 v186, v106, v107
	global_store_dwordx4 v[126:127], v[106:109], off offset:64 nt
	global_store_dwordx2 v[124:125], v[186:187], off offset:32
	v_mul_f32_e32 v107, v107, v107
	v_mul_f32_e32 v109, v109, v109
	v_fmac_f32_e32 v107, v106, v106
	v_fmac_f32_e32 v109, v108, v108
	v_add_f32_e32 v106, v107, v109
	v_add_f32_e32 v106, v110, v106
	s_waitcnt vmcnt(21)
	v_pk_add_f32 v[104:105], v[104:105], v[192:193]
	v_pk_add_f32 v[102:103], v[102:103], v[190:191]
	v_cvt_pk_bf16_f32 v191, v104, v105
	v_cvt_pk_bf16_f32 v190, v102, v103
	global_store_dwordx4 v[126:127], v[102:105], off offset:512 nt
	global_store_dwordx2 v[124:125], v[190:191], off offset:256
	v_mul_f32_e32 v103, v103, v103
	v_mul_f32_e32 v105, v105, v105
	v_fmac_f32_e32 v103, v102, v102
	v_fmac_f32_e32 v105, v104, v104
	v_add_f32_e32 v102, v103, v105
	v_add_f32_e32 v104, v106, v102
	s_waitcnt vmcnt(22)
	v_pk_add_f32 v[102:103], v[100:101], v[196:197]
	v_pk_add_f32 v[100:101], v[98:99], v[194:195]
	v_mul_f32_e32 v99, v103, v103
	v_mul_f32_e32 v98, v101, v101
	v_fmac_f32_e32 v98, v100, v100
	v_fmac_f32_e32 v99, v102, v102
	v_add_f32_e32 v98, v98, v99
	v_add_f32_e32 v98, v104, v98
	ds_bpermute_b32 v99, v118, v98
	global_store_dwordx4 v[126:127], v[100:103], off offset:576 nt
	s_waitcnt lgkmcnt(0)
	v_add_f32_e32 v98, v98, v99
	ds_bpermute_b32 v99, v116, v98
	v_cvt_pk_bf16_f32 v100, v100, v101
	v_cvt_pk_bf16_f32 v101, v102, v103
	global_store_dwordx2 v[124:125], v[100:101], off offset:288
	s_and_saveexec_b64 s[24:25], vcc
	s_cbranch_execz .LBB0_3121
	s_waitcnt lgkmcnt(0)
	v_add_f32_e32 v100, v98, v99
	s_lshl_b32 s26, s4, 2
	v_lshlrev_b64 v[98:99], 7, v[114:115]
	s_ashr_i32 s27, s26, 31
	v_lshl_add_u64 v[98:99], s[10:11], 0, v[98:99]
	v_lshl_add_u64 v[98:99], s[26:27], 2, v[98:99]
	s_lshl_b32 s6, s41, 2
	v_lshl_add_u64 v[98:99], v[98:99], 0, s[6:7]
	global_store_dword v[98:99], v100, off
.LBB0_3121:
	s_or_b64 exec, exec, s[24:25]
	s_mov_b32 s98, 0x100000
	s_mov_b32 s99, 0
	v_lshl_add_u64 v[214:215], v[216:217], 0, s[98:99]
	global_load_dwordx4 v[182:185], v[214:215], off nt
	global_load_dwordx4 v[186:189], v[214:215], off offset:64 nt
	global_load_dwordx4 v[190:193], v[214:215], off offset:512 nt
	global_load_dwordx4 v[194:197], v[214:215], off offset:576 nt
	v_add_u32_e32 v98, 32, v144
	s_waitcnt lgkmcnt(0)
	v_ashrrev_i32_e32 v99, 31, v98
	v_lshlrev_b64 v[100:101], 11, v[98:99]
	v_readlane_b32 s52, v254, 32
	v_lshl_add_u64 v[104:105], v[100:101], 0, v[142:143]
	v_readlane_b32 s66, v254, 46
	v_readlane_b32 s67, v254, 47
	v_readlane_b32 s53, v254, 33
	v_readlane_b32 s54, v254, 34
	v_lshl_add_u64 v[106:107], v[104:105], 2, s[66:67]
	v_lshl_add_u64 v[104:105], v[104:105], 1, s[88:89]
	v_readlane_b32 s55, v254, 35
	v_readlane_b32 s56, v254, 36
	v_readlane_b32 s57, v254, 37
	v_readlane_b32 s58, v254, 38
	v_readlane_b32 s59, v254, 39
	v_readlane_b32 s60, v254, 40
	v_readlane_b32 s61, v254, 41
	v_readlane_b32 s62, v254, 42
	v_readlane_b32 s63, v254, 43
	v_readlane_b32 s64, v254, 44
	v_readlane_b32 s65, v254, 45
	s_waitcnt vmcnt(27)
	v_pk_add_f32 v[96:97], v[96:97], v[200:201]
	v_pk_add_f32 v[94:95], v[94:95], v[198:199]
	v_cvt_pk_bf16_f32 v199, v96, v97
	v_cvt_pk_bf16_f32 v198, v94, v95
	global_store_dwordx4 v[106:107], v[94:97], off nt
	global_store_dwordx2 v[104:105], v[198:199], off
	v_mul_f32_e32 v95, v95, v95
	v_mul_f32_e32 v97, v97, v97
	v_fmac_f32_e32 v95, v94, v94
	v_fmac_f32_e32 v97, v96, v96
	v_add_f32_e32 v94, v95, v97
	s_waitcnt vmcnt(28)
	v_pk_add_f32 v[92:93], v[92:93], v[204:205]
	v_pk_add_f32 v[90:91], v[90:91], v[202:203]
	v_cvt_pk_bf16_f32 v203, v92, v93
	v_cvt_pk_bf16_f32 v202, v90, v91
	global_store_dwordx4 v[106:107], v[90:93], off offset:64 nt
	global_store_dwordx2 v[104:105], v[202:203], off offset:32
	v_mul_f32_e32 v91, v91, v91
	v_mul_f32_e32 v93, v93, v93
	v_fmac_f32_e32 v91, v90, v90
	v_fmac_f32_e32 v93, v92, v92
	v_add_f32_e32 v90, v91, v93
	v_add_f32_e32 v90, v94, v90
	s_waitcnt vmcnt(29)
	v_pk_add_f32 v[88:89], v[88:89], v[208:209]
	v_pk_add_f32 v[86:87], v[86:87], v[206:207]
	v_cvt_pk_bf16_f32 v207, v88, v89
	v_cvt_pk_bf16_f32 v206, v86, v87
	global_store_dwordx4 v[106:107], v[86:89], off offset:512 nt
	global_store_dwordx2 v[104:105], v[206:207], off offset:256
	v_mul_f32_e32 v87, v87, v87
	v_mul_f32_e32 v89, v89, v89
	v_fmac_f32_e32 v87, v86, v86
	v_fmac_f32_e32 v89, v88, v88
	v_add_f32_e32 v86, v87, v89
	v_add_f32_e32 v88, v90, v86
	s_waitcnt vmcnt(30)
	v_pk_add_f32 v[86:87], v[84:85], v[212:213]
	v_pk_add_f32 v[84:85], v[82:83], v[210:211]
	v_mul_f32_e32 v83, v87, v87
	v_mul_f32_e32 v82, v85, v85
	v_fmac_f32_e32 v82, v84, v84
	v_fmac_f32_e32 v83, v86, v86
	v_add_f32_e32 v82, v82, v83
	v_add_f32_e32 v82, v88, v82
	ds_bpermute_b32 v83, v118, v82
	global_store_dwordx4 v[106:107], v[84:87], off offset:576 nt
	s_waitcnt lgkmcnt(0)
	v_add_f32_e32 v82, v82, v83
	ds_bpermute_b32 v83, v116, v82
	v_cvt_pk_bf16_f32 v84, v84, v85
	v_cvt_pk_bf16_f32 v85, v86, v87
	global_store_dwordx2 v[104:105], v[84:85], off offset:288
	s_and_saveexec_b64 s[24:25], vcc
	s_cbranch_execz .LBB0_3123
	s_waitcnt lgkmcnt(0)
	v_add_f32_e32 v84, v82, v83
	s_lshl_b32 s26, s4, 2
	v_lshlrev_b64 v[82:83], 7, v[98:99]
	s_ashr_i32 s27, s26, 31
	v_lshl_add_u64 v[82:83], s[10:11], 0, v[82:83]
	v_lshl_add_u64 v[82:83], s[26:27], 2, v[82:83]
	s_lshl_b32 s6, s41, 2
	v_lshl_add_u64 v[82:83], v[82:83], 0, s[6:7]
	global_store_dword v[82:83], v84, off
.LBB0_3123:
	s_or_b64 exec, exec, s[24:25]
	s_mov_b32 s98, 0x120000
	s_mov_b32 s99, 0
	v_lshl_add_u64 v[214:215], v[216:217], 0, s[98:99]
	global_load_dwordx4 v[198:201], v[214:215], off nt
	global_load_dwordx4 v[202:205], v[214:215], off offset:64 nt
	global_load_dwordx4 v[206:209], v[214:215], off offset:512 nt
	global_load_dwordx4 v[210:213], v[214:215], off offset:576 nt
	v_add_u32_e32 v82, 48, v144
	s_waitcnt lgkmcnt(0)
	v_ashrrev_i32_e32 v83, 31, v82
	v_lshlrev_b64 v[84:85], 11, v[82:83]
	v_readlane_b32 s52, v254, 32
	v_lshl_add_u64 v[88:89], v[84:85], 0, v[142:143]
	v_readlane_b32 s66, v254, 46
	v_readlane_b32 s67, v254, 47
	v_readlane_b32 s53, v254, 33
	v_readlane_b32 s54, v254, 34
	v_lshl_add_u64 v[90:91], v[88:89], 2, s[66:67]
	v_lshl_add_u64 v[88:89], v[88:89], 1, s[88:89]
	v_readlane_b32 s55, v254, 35
	v_readlane_b32 s56, v254, 36
	v_readlane_b32 s57, v254, 37
	v_readlane_b32 s58, v254, 38
	v_readlane_b32 s59, v254, 39
	v_readlane_b32 s60, v254, 40
	v_readlane_b32 s61, v254, 41
	v_readlane_b32 s62, v254, 42
	v_readlane_b32 s63, v254, 43
	v_readlane_b32 s64, v254, 44
	v_readlane_b32 s65, v254, 45
	s_waitcnt vmcnt(27)
	v_pk_add_f32 v[80:81], v[80:81], v[168:169]
	v_pk_add_f32 v[78:79], v[78:79], v[166:167]
	v_cvt_pk_bf16_f32 v167, v80, v81
	v_cvt_pk_bf16_f32 v166, v78, v79
	global_store_dwordx4 v[90:91], v[78:81], off nt
	global_store_dwordx2 v[88:89], v[166:167], off
	v_mul_f32_e32 v79, v79, v79
	v_mul_f32_e32 v81, v81, v81
	v_fmac_f32_e32 v79, v78, v78
	v_fmac_f32_e32 v81, v80, v80
	v_add_f32_e32 v78, v79, v81
	s_waitcnt vmcnt(28)
	v_pk_add_f32 v[76:77], v[76:77], v[172:173]
	v_pk_add_f32 v[74:75], v[74:75], v[170:171]
	v_cvt_pk_bf16_f32 v171, v76, v77
	v_cvt_pk_bf16_f32 v170, v74, v75
	global_store_dwordx4 v[90:91], v[74:77], off offset:64 nt
	global_store_dwordx2 v[88:89], v[170:171], off offset:32
	v_mul_f32_e32 v75, v75, v75
	v_mul_f32_e32 v77, v77, v77
	v_fmac_f32_e32 v75, v74, v74
	v_fmac_f32_e32 v77, v76, v76
	v_add_f32_e32 v74, v75, v77
	v_add_f32_e32 v74, v78, v74
	s_waitcnt vmcnt(29)
	v_pk_add_f32 v[72:73], v[72:73], v[176:177]
	v_pk_add_f32 v[70:71], v[70:71], v[174:175]
	v_cvt_pk_bf16_f32 v175, v72, v73
	v_cvt_pk_bf16_f32 v174, v70, v71
	global_store_dwordx4 v[90:91], v[70:73], off offset:512 nt
	global_store_dwordx2 v[88:89], v[174:175], off offset:256
	v_mul_f32_e32 v71, v71, v71
	v_mul_f32_e32 v73, v73, v73
	v_fmac_f32_e32 v71, v70, v70
	v_fmac_f32_e32 v73, v72, v72
	v_add_f32_e32 v70, v71, v73
	v_add_f32_e32 v72, v74, v70
	s_waitcnt vmcnt(30)
	v_pk_add_f32 v[70:71], v[68:69], v[180:181]
	v_pk_add_f32 v[68:69], v[66:67], v[178:179]
	v_mul_f32_e32 v67, v71, v71
	v_mul_f32_e32 v66, v69, v69
	v_fmac_f32_e32 v66, v68, v68
	v_fmac_f32_e32 v67, v70, v70
	v_add_f32_e32 v66, v66, v67
	v_add_f32_e32 v66, v72, v66
	ds_bpermute_b32 v67, v118, v66
	global_store_dwordx4 v[90:91], v[68:71], off offset:576 nt
	s_waitcnt lgkmcnt(0)
	v_add_f32_e32 v66, v66, v67
	ds_bpermute_b32 v67, v116, v66
	v_cvt_pk_bf16_f32 v68, v68, v69
	v_cvt_pk_bf16_f32 v69, v70, v71
	global_store_dwordx2 v[88:89], v[68:69], off offset:288
	s_and_saveexec_b64 s[24:25], vcc
	s_cbranch_execz .LBB0_3125
	s_waitcnt lgkmcnt(0)
	v_add_f32_e32 v68, v66, v67
	s_lshl_b32 s26, s4, 2
	v_lshlrev_b64 v[66:67], 7, v[82:83]
	s_ashr_i32 s27, s26, 31
	v_lshl_add_u64 v[66:67], s[10:11], 0, v[66:67]
	v_lshl_add_u64 v[66:67], s[26:27], 2, v[66:67]
	s_lshl_b32 s6, s41, 2
	v_lshl_add_u64 v[66:67], v[66:67], 0, s[6:7]
	global_store_dword v[66:67], v68, off
.LBB0_3125:
	s_or_b64 exec, exec, s[24:25]
	s_mov_b32 s98, 0x140000
	s_mov_b32 s99, 0
	v_lshl_add_u64 v[214:215], v[216:217], 0, s[98:99]
	global_load_dwordx4 v[166:169], v[214:215], off nt
	global_load_dwordx4 v[170:173], v[214:215], off offset:64 nt
	global_load_dwordx4 v[174:177], v[214:215], off offset:512 nt
	global_load_dwordx4 v[178:181], v[214:215], off offset:576 nt
	v_add_u32_e32 v66, 0x80, v144
	s_waitcnt lgkmcnt(0)
	v_ashrrev_i32_e32 v67, 31, v66
	v_lshlrev_b64 v[68:69], 11, v[66:67]
	v_readlane_b32 s52, v254, 32
	v_lshl_add_u64 v[72:73], v[68:69], 0, v[142:143]
	v_readlane_b32 s66, v254, 46
	v_readlane_b32 s67, v254, 47
	v_readlane_b32 s53, v254, 33
	v_readlane_b32 s54, v254, 34
	v_lshl_add_u64 v[74:75], v[72:73], 2, s[66:67]
	v_lshl_add_u64 v[72:73], v[72:73], 1, s[88:89]
	v_readlane_b32 s55, v254, 35
	v_readlane_b32 s56, v254, 36
	v_readlane_b32 s57, v254, 37
	v_readlane_b32 s58, v254, 38
	v_readlane_b32 s59, v254, 39
	v_readlane_b32 s60, v254, 40
	v_readlane_b32 s61, v254, 41
	v_readlane_b32 s62, v254, 42
	v_readlane_b32 s63, v254, 43
	v_readlane_b32 s64, v254, 44
	v_readlane_b32 s65, v254, 45
	s_waitcnt vmcnt(27)
	v_pk_add_f32 v[64:65], v[64:65], v[184:185]
	v_pk_add_f32 v[62:63], v[62:63], v[182:183]
	v_cvt_pk_bf16_f32 v183, v64, v65
	v_cvt_pk_bf16_f32 v182, v62, v63
	global_store_dwordx4 v[74:75], v[62:65], off nt
	global_store_dwordx2 v[72:73], v[182:183], off
	v_mul_f32_e32 v63, v63, v63
	v_mul_f32_e32 v65, v65, v65
	v_fmac_f32_e32 v63, v62, v62
	v_fmac_f32_e32 v65, v64, v64
	v_add_f32_e32 v62, v63, v65
	s_waitcnt vmcnt(28)
	v_pk_add_f32 v[60:61], v[60:61], v[188:189]
	v_pk_add_f32 v[58:59], v[58:59], v[186:187]
	v_cvt_pk_bf16_f32 v187, v60, v61
	v_cvt_pk_bf16_f32 v186, v58, v59
	global_store_dwordx4 v[74:75], v[58:61], off offset:64 nt
	global_store_dwordx2 v[72:73], v[186:187], off offset:32
	v_mul_f32_e32 v59, v59, v59
	v_mul_f32_e32 v61, v61, v61
	v_fmac_f32_e32 v59, v58, v58
	v_fmac_f32_e32 v61, v60, v60
	v_add_f32_e32 v58, v59, v61
	v_add_f32_e32 v58, v62, v58
	s_waitcnt vmcnt(29)
	v_pk_add_f32 v[56:57], v[56:57], v[192:193]
	v_pk_add_f32 v[54:55], v[54:55], v[190:191]
	v_cvt_pk_bf16_f32 v191, v56, v57
	v_cvt_pk_bf16_f32 v190, v54, v55
	global_store_dwordx4 v[74:75], v[54:57], off offset:512 nt
	global_store_dwordx2 v[72:73], v[190:191], off offset:256
	v_mul_f32_e32 v55, v55, v55
	v_mul_f32_e32 v57, v57, v57
	v_fmac_f32_e32 v55, v54, v54
	v_fmac_f32_e32 v57, v56, v56
	v_add_f32_e32 v54, v55, v57
	v_add_f32_e32 v56, v58, v54
	s_waitcnt vmcnt(30)
	v_pk_add_f32 v[54:55], v[52:53], v[196:197]
	v_pk_add_f32 v[52:53], v[50:51], v[194:195]
	v_mul_f32_e32 v51, v55, v55
	v_mul_f32_e32 v50, v53, v53
	v_fmac_f32_e32 v50, v52, v52
	v_fmac_f32_e32 v51, v54, v54
	v_add_f32_e32 v50, v50, v51
	v_add_f32_e32 v50, v56, v50
	ds_bpermute_b32 v51, v118, v50
	global_store_dwordx4 v[74:75], v[52:55], off offset:576 nt
	s_waitcnt lgkmcnt(0)
	v_add_f32_e32 v50, v50, v51
	ds_bpermute_b32 v51, v116, v50
	v_cvt_pk_bf16_f32 v52, v52, v53
	v_cvt_pk_bf16_f32 v53, v54, v55
	global_store_dwordx2 v[72:73], v[52:53], off offset:288
	s_and_saveexec_b64 s[24:25], vcc
	s_cbranch_execz .LBB0_3127
	s_waitcnt lgkmcnt(0)
	v_add_f32_e32 v52, v50, v51
	s_lshl_b32 s26, s4, 2
	v_lshlrev_b64 v[50:51], 7, v[66:67]
	s_ashr_i32 s27, s26, 31
	v_lshl_add_u64 v[50:51], s[10:11], 0, v[50:51]
	v_lshl_add_u64 v[50:51], s[26:27], 2, v[50:51]
	s_lshl_b32 s6, s41, 2
	v_lshl_add_u64 v[50:51], v[50:51], 0, s[6:7]
	global_store_dword v[50:51], v52, off
.LBB0_3127:
	s_or_b64 exec, exec, s[24:25]
	s_mov_b32 s98, 0x160000
	s_mov_b32 s99, 0
	v_lshl_add_u64 v[214:215], v[216:217], 0, s[98:99]
	global_load_dwordx4 v[182:185], v[214:215], off nt
	global_load_dwordx4 v[186:189], v[214:215], off offset:64 nt
	global_load_dwordx4 v[190:193], v[214:215], off offset:512 nt
	global_load_dwordx4 v[194:197], v[214:215], off offset:576 nt
	v_add_u32_e32 v50, 0x90, v144
	s_waitcnt lgkmcnt(0)
	v_ashrrev_i32_e32 v51, 31, v50
	v_lshlrev_b64 v[52:53], 11, v[50:51]
	v_readlane_b32 s52, v254, 32
	v_lshl_add_u64 v[56:57], v[52:53], 0, v[142:143]
	v_readlane_b32 s66, v254, 46
	v_readlane_b32 s67, v254, 47
	v_readlane_b32 s53, v254, 33
	v_readlane_b32 s54, v254, 34
	v_lshl_add_u64 v[58:59], v[56:57], 2, s[66:67]
	v_lshl_add_u64 v[56:57], v[56:57], 1, s[88:89]
	v_readlane_b32 s55, v254, 35
	v_readlane_b32 s56, v254, 36
	v_readlane_b32 s57, v254, 37
	v_readlane_b32 s58, v254, 38
	v_readlane_b32 s59, v254, 39
	v_readlane_b32 s60, v254, 40
	v_readlane_b32 s61, v254, 41
	v_readlane_b32 s62, v254, 42
	v_readlane_b32 s63, v254, 43
	v_readlane_b32 s64, v254, 44
	v_readlane_b32 s65, v254, 45
	s_waitcnt vmcnt(27)
	v_pk_add_f32 v[48:49], v[48:49], v[200:201]
	v_pk_add_f32 v[46:47], v[46:47], v[198:199]
	v_cvt_pk_bf16_f32 v199, v48, v49
	v_cvt_pk_bf16_f32 v198, v46, v47
	global_store_dwordx4 v[58:59], v[46:49], off nt
	global_store_dwordx2 v[56:57], v[198:199], off
	v_mul_f32_e32 v47, v47, v47
	v_mul_f32_e32 v49, v49, v49
	v_fmac_f32_e32 v47, v46, v46
	v_fmac_f32_e32 v49, v48, v48
	v_add_f32_e32 v46, v47, v49
	s_waitcnt vmcnt(28)
	v_pk_add_f32 v[44:45], v[44:45], v[204:205]
	v_pk_add_f32 v[42:43], v[42:43], v[202:203]
	v_cvt_pk_bf16_f32 v203, v44, v45
	v_cvt_pk_bf16_f32 v202, v42, v43
	global_store_dwordx4 v[58:59], v[42:45], off offset:64 nt
	global_store_dwordx2 v[56:57], v[202:203], off offset:32
	v_mul_f32_e32 v43, v43, v43
	v_mul_f32_e32 v45, v45, v45
	v_fmac_f32_e32 v43, v42, v42
	v_fmac_f32_e32 v45, v44, v44
	v_add_f32_e32 v42, v43, v45
	v_add_f32_e32 v42, v46, v42
	s_waitcnt vmcnt(29)
	v_pk_add_f32 v[40:41], v[40:41], v[208:209]
	v_pk_add_f32 v[38:39], v[38:39], v[206:207]
	v_cvt_pk_bf16_f32 v207, v40, v41
	v_cvt_pk_bf16_f32 v206, v38, v39
	global_store_dwordx4 v[58:59], v[38:41], off offset:512 nt
	global_store_dwordx2 v[56:57], v[206:207], off offset:256
	v_mul_f32_e32 v39, v39, v39
	v_mul_f32_e32 v41, v41, v41
	v_fmac_f32_e32 v39, v38, v38
	v_fmac_f32_e32 v41, v40, v40
	v_add_f32_e32 v38, v39, v41
	v_add_f32_e32 v40, v42, v38
	s_waitcnt vmcnt(30)
	v_pk_add_f32 v[38:39], v[36:37], v[212:213]
	v_pk_add_f32 v[36:37], v[34:35], v[210:211]
	v_mul_f32_e32 v35, v39, v39
	v_mul_f32_e32 v34, v37, v37
	v_fmac_f32_e32 v34, v36, v36
	v_fmac_f32_e32 v35, v38, v38
	v_add_f32_e32 v34, v34, v35
	v_add_f32_e32 v34, v40, v34
	ds_bpermute_b32 v35, v118, v34
	global_store_dwordx4 v[58:59], v[36:39], off offset:576 nt
	s_waitcnt lgkmcnt(0)
	v_add_f32_e32 v34, v34, v35
	ds_bpermute_b32 v35, v116, v34
	v_cvt_pk_bf16_f32 v36, v36, v37
	v_cvt_pk_bf16_f32 v37, v38, v39
	global_store_dwordx2 v[56:57], v[36:37], off offset:288
	s_and_saveexec_b64 s[24:25], vcc
	s_cbranch_execz .LBB0_3129
	s_waitcnt lgkmcnt(0)
	v_add_f32_e32 v36, v34, v35
	s_lshl_b32 s26, s4, 2
	v_lshlrev_b64 v[34:35], 7, v[50:51]
	s_ashr_i32 s27, s26, 31
	v_lshl_add_u64 v[34:35], s[10:11], 0, v[34:35]
	v_lshl_add_u64 v[34:35], s[26:27], 2, v[34:35]
	s_lshl_b32 s6, s41, 2
	v_lshl_add_u64 v[34:35], v[34:35], 0, s[6:7]
	global_store_dword v[34:35], v36, off
.LBB0_3129:
	s_or_b64 exec, exec, s[24:25]
	v_add_u32_e32 v34, 0xa0, v144
	s_waitcnt lgkmcnt(0)
	v_ashrrev_i32_e32 v35, 31, v34
	v_lshlrev_b64 v[36:37], 11, v[34:35]
	v_readlane_b32 s52, v254, 32
	v_lshl_add_u64 v[40:41], v[36:37], 0, v[142:143]
	v_readlane_b32 s66, v254, 46
	v_readlane_b32 s67, v254, 47
	v_readlane_b32 s53, v254, 33
	v_readlane_b32 s54, v254, 34
	v_lshl_add_u64 v[42:43], v[40:41], 2, s[66:67]
	v_lshl_add_u64 v[40:41], v[40:41], 1, s[88:89]
	v_readlane_b32 s55, v254, 35
	v_readlane_b32 s56, v254, 36
	v_readlane_b32 s57, v254, 37
	v_readlane_b32 s58, v254, 38
	v_readlane_b32 s59, v254, 39
	v_readlane_b32 s60, v254, 40
	v_readlane_b32 s61, v254, 41
	v_readlane_b32 s62, v254, 42
	v_readlane_b32 s63, v254, 43
	v_readlane_b32 s64, v254, 44
	v_readlane_b32 s65, v254, 45
	s_waitcnt vmcnt(23)
	v_pk_add_f32 v[32:33], v[32:33], v[168:169]
	v_pk_add_f32 v[30:31], v[30:31], v[166:167]
	v_cvt_pk_bf16_f32 v167, v32, v33
	v_cvt_pk_bf16_f32 v166, v30, v31
	global_store_dwordx4 v[42:43], v[30:33], off nt
	global_store_dwordx2 v[40:41], v[166:167], off
	v_mul_f32_e32 v31, v31, v31
	v_mul_f32_e32 v33, v33, v33
	v_fmac_f32_e32 v31, v30, v30
	v_fmac_f32_e32 v33, v32, v32
	v_add_f32_e32 v30, v31, v33
	s_waitcnt vmcnt(24)
	v_pk_add_f32 v[28:29], v[28:29], v[172:173]
	v_pk_add_f32 v[26:27], v[26:27], v[170:171]
	v_cvt_pk_bf16_f32 v171, v28, v29
	v_cvt_pk_bf16_f32 v170, v26, v27
	global_store_dwordx4 v[42:43], v[26:29], off offset:64 nt
	global_store_dwordx2 v[40:41], v[170:171], off offset:32
	v_mul_f32_e32 v27, v27, v27
	v_mul_f32_e32 v29, v29, v29
	v_fmac_f32_e32 v27, v26, v26
	v_fmac_f32_e32 v29, v28, v28
	v_add_f32_e32 v26, v27, v29
	v_add_f32_e32 v26, v30, v26
	s_waitcnt vmcnt(25)
	v_pk_add_f32 v[24:25], v[24:25], v[176:177]
	v_pk_add_f32 v[22:23], v[22:23], v[174:175]
	v_cvt_pk_bf16_f32 v175, v24, v25
	v_cvt_pk_bf16_f32 v174, v22, v23
	global_store_dwordx4 v[42:43], v[22:25], off offset:512 nt
	global_store_dwordx2 v[40:41], v[174:175], off offset:256
	v_mul_f32_e32 v23, v23, v23
	v_mul_f32_e32 v25, v25, v25
	v_fmac_f32_e32 v23, v22, v22
	v_fmac_f32_e32 v25, v24, v24
	v_add_f32_e32 v22, v23, v25
	v_add_f32_e32 v24, v26, v22
	s_waitcnt vmcnt(26)
	v_pk_add_f32 v[22:23], v[20:21], v[180:181]
	v_pk_add_f32 v[20:21], v[18:19], v[178:179]
	v_mul_f32_e32 v19, v23, v23
	v_mul_f32_e32 v18, v21, v21
	v_fmac_f32_e32 v18, v20, v20
	v_fmac_f32_e32 v19, v22, v22
	v_add_f32_e32 v18, v18, v19
	v_add_f32_e32 v18, v24, v18
	ds_bpermute_b32 v19, v118, v18
	global_store_dwordx4 v[42:43], v[20:23], off offset:576 nt
	s_waitcnt lgkmcnt(0)
	v_add_f32_e32 v18, v18, v19
	ds_bpermute_b32 v19, v116, v18
	v_cvt_pk_bf16_f32 v20, v20, v21
	v_cvt_pk_bf16_f32 v21, v22, v23
	global_store_dwordx2 v[40:41], v[20:21], off offset:288
	s_and_saveexec_b64 s[24:25], vcc
	s_cbranch_execz .LBB0_3131
	s_waitcnt lgkmcnt(0)
	v_add_f32_e32 v20, v18, v19
	s_lshl_b32 s26, s4, 2
	v_lshlrev_b64 v[18:19], 7, v[34:35]
	s_ashr_i32 s27, s26, 31
	v_lshl_add_u64 v[18:19], s[10:11], 0, v[18:19]
	v_lshl_add_u64 v[18:19], s[26:27], 2, v[18:19]
	s_lshl_b32 s6, s41, 2
	v_lshl_add_u64 v[18:19], v[18:19], 0, s[6:7]
	global_store_dword v[18:19], v20, off
.LBB0_3131:
	s_or_b64 exec, exec, s[24:25]
	v_add_u32_e32 v18, 0xb0, v144
	s_waitcnt lgkmcnt(0)
	v_ashrrev_i32_e32 v19, 31, v18
	v_lshlrev_b64 v[20:21], 11, v[18:19]
	v_readlane_b32 s52, v254, 32
	v_lshl_add_u64 v[24:25], v[20:21], 0, v[142:143]
	v_readlane_b32 s66, v254, 46
	v_readlane_b32 s67, v254, 47
	v_readlane_b32 s53, v254, 33
	v_readlane_b32 s54, v254, 34
	v_lshl_add_u64 v[26:27], v[24:25], 2, s[66:67]
	v_lshl_add_u64 v[24:25], v[24:25], 1, s[88:89]
	v_readlane_b32 s55, v254, 35
	v_readlane_b32 s56, v254, 36
	v_readlane_b32 s57, v254, 37
	v_readlane_b32 s58, v254, 38
	v_readlane_b32 s59, v254, 39
	v_readlane_b32 s60, v254, 40
	v_readlane_b32 s61, v254, 41
	v_readlane_b32 s62, v254, 42
	v_readlane_b32 s63, v254, 43
	v_readlane_b32 s64, v254, 44
	v_readlane_b32 s65, v254, 45
	s_waitcnt vmcnt(19)
	v_pk_add_f32 v[16:17], v[16:17], v[184:185]
	v_pk_add_f32 v[14:15], v[14:15], v[182:183]
	v_cvt_pk_bf16_f32 v183, v16, v17
	v_cvt_pk_bf16_f32 v182, v14, v15
	global_store_dwordx4 v[26:27], v[14:17], off nt
	global_store_dwordx2 v[24:25], v[182:183], off
	v_mul_f32_e32 v15, v15, v15
	v_mul_f32_e32 v17, v17, v17
	v_fmac_f32_e32 v15, v14, v14
	v_fmac_f32_e32 v17, v16, v16
	v_add_f32_e32 v14, v15, v17
	s_waitcnt vmcnt(20)
	v_pk_add_f32 v[12:13], v[12:13], v[188:189]
	v_pk_add_f32 v[10:11], v[10:11], v[186:187]
	v_cvt_pk_bf16_f32 v187, v12, v13
	v_cvt_pk_bf16_f32 v186, v10, v11
	global_store_dwordx4 v[26:27], v[10:13], off offset:64 nt
	global_store_dwordx2 v[24:25], v[186:187], off offset:32
	v_mul_f32_e32 v11, v11, v11
	v_mul_f32_e32 v13, v13, v13
	v_fmac_f32_e32 v11, v10, v10
	v_fmac_f32_e32 v13, v12, v12
	v_add_f32_e32 v10, v11, v13
	v_add_f32_e32 v10, v14, v10
	s_waitcnt vmcnt(21)
	v_pk_add_f32 v[8:9], v[8:9], v[192:193]
	v_pk_add_f32 v[6:7], v[6:7], v[190:191]
	v_cvt_pk_bf16_f32 v191, v8, v9
	v_cvt_pk_bf16_f32 v190, v6, v7
	global_store_dwordx4 v[26:27], v[6:9], off offset:512 nt
	global_store_dwordx2 v[24:25], v[190:191], off offset:256
	v_mul_f32_e32 v7, v7, v7
	v_mul_f32_e32 v9, v9, v9
	v_fmac_f32_e32 v7, v6, v6
	v_fmac_f32_e32 v9, v8, v8
	v_add_f32_e32 v6, v7, v9
	v_add_f32_e32 v8, v10, v6
	s_waitcnt vmcnt(22)
	v_pk_add_f32 v[6:7], v[4:5], v[196:197]
	v_pk_add_f32 v[4:5], v[2:3], v[194:195]
	v_mul_f32_e32 v3, v7, v7
	v_mul_f32_e32 v2, v5, v5
	v_fmac_f32_e32 v2, v4, v4
	v_fmac_f32_e32 v3, v6, v6
	v_add_f32_e32 v2, v2, v3
	v_add_f32_e32 v2, v8, v2
	ds_bpermute_b32 v3, v118, v2
	global_store_dwordx4 v[26:27], v[4:7], off offset:576 nt
	s_waitcnt lgkmcnt(0)
	v_add_f32_e32 v2, v2, v3
	ds_bpermute_b32 v3, v116, v2
	v_cvt_pk_bf16_f32 v4, v4, v5
	v_cvt_pk_bf16_f32 v5, v6, v7
	global_store_dwordx2 v[24:25], v[4:5], off offset:288
	s_and_saveexec_b64 s[24:25], vcc
	s_cbranch_execz .LBB0_3133
	s_waitcnt lgkmcnt(0)
	v_add_f32_e32 v4, v2, v3
	s_lshl_b32 s26, s4, 2
	v_lshlrev_b64 v[2:3], 7, v[18:19]
	s_ashr_i32 s27, s26, 31
	v_lshl_add_u64 v[2:3], s[10:11], 0, v[2:3]
	v_lshl_add_u64 v[2:3], s[26:27], 2, v[2:3]
	s_lshl_b32 s6, s41, 2
	v_lshl_add_u64 v[2:3], v[2:3], 0, s[6:7]
	global_store_dword v[2:3], v4, off
